# mixa latent attention: key-block loop unrolled x2 with a second register staging set (K/V loads issued two iterations ahead)
# baseline (speedup 1.0000x reference)
.LBB0_346:
	s_and_b64 vcc, exec, s[20:21]
	s_cbranch_vccz .LBB0_313
	s_and_b32 s101, s8, 7
	s_lshr_b32 s100, s8, 3
	s_and_b32 s99, s101, 1
	s_lshl_b32 s99, s99, 1
	s_and_b32 s98, s100, 1
	s_or_b32 s99, s99, s98
	s_lshl_b32 s99, s99, 2
	s_bfe_u32 s98, s100, 0x20001
	s_or_b32 s99, s99, s98
	s_lshl_b32 s99, s99, 3
	s_lshr_b32 s98, s100, 3
	s_or_b32 s99, s99, s98
	s_lshr_b32 s101, s101, 1
	s_lshl_b32 s101, s101, 7
	s_or_b32 s101, s101, s99
	s_ashr_i32 s9, s101, 7
	s_bfe_u32 s24, s101, 0x40003
	s_lshl_b32 s16, s9, 10
	s_ashr_i32 s22, s9, 31
	s_mul_i32 s21, s9, 0xc0000
	s_mul_hi_i32 s20, s9, 0xc0000
	s_add_u32 s21, s33, s21
	s_addc_u32 s23, s30, s20
	s_lshl_b32 s20, s101, 1
	s_and_b32 s25, s20, 0xc0
	s_lshl_b32 s20, s25, 1
	s_add_u32 s20, s21, s20
	s_addc_u32 s21, s23, 0
	s_lshl_b32 s9, s9, 8
	s_or_b32 s9, s9, s25
	s_mul_hi_u32 s23, s9, 0xc00
	s_mulk_i32 s22, 0xc00
	s_add_i32 s23, s23, s22
	s_mulk_i32 s9, 0xc00
	s_add_u32 s22, s31, s9
	s_addc_u32 s23, s34, s23
	s_lshl_b32 s9, s101, 7
	s_and_b32 s9, s9, 0x380
	s_or_b32 s9, s16, s9
	v_add_u32_e32 v114, s9, v150
	v_ashrrev_i32_e32 v115, 31, v114
	v_lshlrev_b64 v[2:3], 11, v[114:115]
	v_mov_b32_e32 v107, v67
	v_lshl_add_u64 v[2:3], s[14:15], 0, v[2:3]
	s_lshl_b32 s16, s24, 7
	v_lshl_add_u64 v[4:5], s[22:23], 0, v[106:107]
	v_mov_b32_e32 v109, v67
	v_lshl_add_u64 v[2:3], v[2:3], 0, s[16:17]
	v_lshl_add_u64 v[118:119], v[4:5], 0, v[108:109]
	v_lshlrev_b32_e32 v66, 1, v68
	v_lshl_add_u64 v[116:117], s[20:21], 0, v[106:107]
	v_add_co_u32_e32 v10, vcc, s96, v118
	v_lshl_add_u64 v[2:3], v[2:3], 0, v[66:67]
	v_mov_b32_e32 v105, v67
	v_lshl_add_u64 v[18:19], v[116:117], 0, v[70:71]
	v_lshl_add_u64 v[4:5], v[116:117], 0, v[72:73]
	v_addc_co_u32_e32 v11, vcc, 0, v119, vcc
	v_lshl_add_u64 v[2:3], v[2:3], 0, v[104:105]
	s_mov_b32 s9, 0x8000
	global_load_dwordx4 v[6:9], v[4:5], off
	s_nop 0
	global_load_dwordx4 v[10:13], v[10:11], off
	s_nop 0
	global_load_dwordx4 v[14:17], v[118:119], off
	s_nop 0
	global_load_dwordx4 v[18:21], v[18:19], off
	v_add_co_u32_e32 v4, vcc, s9, v2
	v_mov_b32_e32 v111, v67
	s_nop 0
	v_addc_co_u32_e32 v5, vcc, 0, v3, vcc
	global_load_dwordx4 v[34:37], v[2:3], off
	global_load_dwordx4 v[38:41], v[4:5], off offset:64
	global_load_dwordx4 v[42:45], v[2:3], off offset:64
	global_load_dwordx4 v[46:49], v[4:5], off
	v_lshl_add_u64 v[2:3], v[116:117], 0, v[110:111]
	v_add_co_u32_e32 v4, vcc, s9, v2
	s_mov_b32 s9, 0xc000
	s_nop 0
	v_addc_co_u32_e32 v5, vcc, 0, v3, vcc
	v_lshl_add_u64 v[22:23], s[22:23], 0, v[108:109]
	v_add_co_u32_e32 v2, vcc, s9, v2
	v_lshl_add_u64 v[22:23], v[22:23], 0, v[106:107]
	s_nop 0
	v_addc_co_u32_e32 v3, vcc, 0, v3, vcc
	s_barrier
	global_load_dwordx4 v[50:53], v[4:5], off
	global_load_dwordx4 v[54:57], v[22:23], off offset:128
	v_add_co_u32_e32 v4, vcc, s96, v22
	v_xor_b32_e32 v22, 16, v156
	s_nop 0
	v_addc_co_u32_e32 v5, vcc, 0, v23, vcc
	global_load_dwordx4 v[58:61], v[2:3], off
	global_load_dwordx4 v[62:65], v[4:5], off offset:128
	v_lshlrev_b32_e32 v224, 9, v152
	v_mov_b32_e32 v225, 0
	v_lshl_add_u64 v[224:225], v[116:117], 0, v[224:225]
	v_mov_b32_e32 v228, v118
	v_mov_b32_e32 v229, v119
	global_load_dwordx4 v[216:219], v[224:225], off
	global_load_dwordx4 v[220:223], v[228:229], off offset:256
	v_add_co_u32_e32 v224, vcc, s19, v224
	s_nop 1
	v_addc_co_u32_e32 v225, vcc, 0, v225, vcc
	v_add_co_u32_e32 v228, vcc, s96, v228
	s_nop 1
	v_addc_co_u32_e32 v229, vcc, 0, v229, vcc
	global_load_dwordx4 v[224:227], v[224:225], off
	global_load_dwordx4 v[228:231], v[228:229], off offset:256
	v_and_b32_e32 v3, 64, v156
	v_add_u32_e32 v24, 64, v3
	v_xor_b32_e32 v23, 32, v156
	v_cmp_lt_i32_e32 vcc, v22, v24
	v_mov_b32_e32 v2, 0
	s_mov_b32 s21, 0
	v_cndmask_b32_e32 v22, v156, v22, vcc
	v_cmp_lt_i32_e32 vcc, v23, v24
	v_mov_b32_e32 v95, 0xf149f2ca
	v_mov_b32_e32 v3, v2
	v_cndmask_b32_e32 v23, v156, v23, vcc
	v_mov_b32_e32 v4, v2
	v_mov_b32_e32 v5, v2
	v_lshlrev_b32_e32 v89, 2, v22
	v_lshlrev_b32_e32 v87, 2, v23
	s_lshl_b32 s9, s24, 6
	v_mov_b32_e32 v26, v2
	v_mov_b32_e32 v27, v2
	v_mov_b32_e32 v28, v2
	v_mov_b32_e32 v29, v2
	v_mov_b32_e32 v22, v2
	s_waitcnt vmcnt(15)
	ds_write_b128 v142, v[6:9] offset:4608
	s_waitcnt vmcnt(14)
	ds_write_b128 v142, v[10:13] offset:13824
	s_waitcnt vmcnt(13)
	ds_write_b128 v142, v[14:17] offset:9216
	s_waitcnt vmcnt(12)
	ds_write_b128 v142, v[18:21]
	v_mov_b32_e32 v18, v2
	v_mov_b32_e32 v19, v2
	v_mov_b32_e32 v20, v2
	v_mov_b32_e32 v21, v2
	v_mov_b32_e32 v6, v2
	v_mov_b32_e32 v7, v2
	v_mov_b32_e32 v8, v2
	v_mov_b32_e32 v9, v2
	v_mov_b32_e32 v23, v2
	v_mov_b32_e32 v24, v2
	v_mov_b32_e32 v25, v2
	v_mov_b32_e32 v10, v2
	v_mov_b32_e32 v11, v2
	v_mov_b32_e32 v12, v2
	v_mov_b32_e32 v13, v2
	v_mov_b32_e32 v30, v2
	v_mov_b32_e32 v31, v2
	v_mov_b32_e32 v32, v2
	v_mov_b32_e32 v33, v2
	v_mov_b32_e32 v14, v2
	v_mov_b32_e32 v15, v2
	v_mov_b32_e32 v16, v2
	v_mov_b32_e32 v17, v2
	v_mov_b32_e32 v112, v2
	v_mov_b32_e32 v113, v2
	v_mov_b32_e32 v93, 0xf149f2ca
	s_waitcnt lgkmcnt(0)
	s_barrier
.LBB0_348:
	s_add_i32 s20, s21, 1
	s_bitcmp1_b32 s20, 0
	s_cselect_b32 s16, 0x4800, 0
	v_add_u32_e32 v66, s16, v69
	s_min_i32 s16, s20, 21
	s_lshl_b32 s22, s16, 6
	s_waitcnt vmcnt(7)
	ds_write_b128 v66, v[50:53]
	s_waitcnt vmcnt(6)
	ds_write_b128 v66, v[54:57] offset:9216
	s_waitcnt vmcnt(5)
	ds_write_b128 v66, v[58:61] offset:4608
	s_waitcnt vmcnt(4)
	ds_write_b128 v66, v[62:65] offset:13824
	v_add_lshl_u32 v66, s22, v152, 9
	s_lshl_b32 s16, s16, 7
	v_lshl_add_u64 v[58:59], v[116:117], 0, v[66:67]
	v_lshl_add_u64 v[62:63], v[118:119], 0, s[16:17]
	s_bitcmp1_b32 s21, 0
	global_load_dwordx4 v[50:53], v[58:59], off
	global_load_dwordx4 v[54:57], v[62:63], off offset:256
	v_add_co_u32_e32 v58, vcc, s19, v58
	s_cselect_b32 s16, 0x4800, 0
	s_nop 0
	v_addc_co_u32_e32 v59, vcc, 0, v59, vcc
	s_add_i32 s16, s16, 32
	v_add_co_u32_e32 v62, vcc, s96, v62
	v_add_u32_e32 v97, s16, v151
	s_nop 0
	v_addc_co_u32_e32 v63, vcc, 0, v63, vcc
	v_lshl_add_u32 v66, v68, 1, v97
	global_load_dwordx4 v[58:61], v[58:59], off
	s_cmp_lg_u32 s20, 24
	global_load_dwordx4 v[62:65], v[62:63], off offset:256
	ds_read_b128 v[158:161], v66
	ds_read_b128 v[162:165], v66 offset:64
	s_waitcnt lgkmcnt(1)
	v_mfma_f32_16x16x32_bf16 v[166:169], v[158:161], v[34:37], 0
	s_mov_b32 s21, s20
	v_mfma_f32_16x16x32_bf16 v[158:161], v[158:161], v[46:49], 0
	s_waitcnt lgkmcnt(0)
	v_mfma_f32_16x16x32_bf16 v[166:169], v[162:165], v[42:45], v[166:169]
	v_mfma_f32_16x16x32_bf16 v[158:161], v[162:165], v[38:41], v[158:161]
	ds_read_b128 v[162:165], v66 offset:2304
	ds_read_b128 v[170:173], v66 offset:2368
	s_nop 4
	v_mul_f32_e32 v91, 0x3fb8aa3b, v167
	v_mul_f32_e32 v99, 0x3fb8aa3b, v169
	s_waitcnt lgkmcnt(1)
	v_mfma_f32_16x16x32_bf16 v[174:177], v[162:165], v[34:37], 0
	v_mfma_f32_16x16x32_bf16 v[162:165], v[162:165], v[46:49], 0
	s_waitcnt lgkmcnt(0)
	v_mfma_f32_16x16x32_bf16 v[174:177], v[170:173], v[42:45], v[174:177]
	v_mfma_f32_16x16x32_bf16 v[162:165], v[170:173], v[38:41], v[162:165]
	ds_read_b128 v[170:173], v66 offset:4608
	ds_read_b128 v[188:191], v66 offset:4672
	s_waitcnt lgkmcnt(1)
	v_mfma_f32_16x16x32_bf16 v[192:195], v[170:173], v[34:37], 0
	v_mfma_f32_16x16x32_bf16 v[170:173], v[170:173], v[46:49], 0
	s_waitcnt lgkmcnt(0)
	v_mfma_f32_16x16x32_bf16 v[192:195], v[188:191], v[42:45], v[192:195]
	v_mfma_f32_16x16x32_bf16 v[170:173], v[188:191], v[38:41], v[170:173]
	ds_read_b128 v[188:191], v66 offset:6912
	ds_read_b128 v[196:199], v66 offset:6976
	v_mul_f32_e32 v66, 0x3fb8aa3b, v166
	v_max3_f32 v66, v66, s97, v91
	s_waitcnt lgkmcnt(1)
	v_mfma_f32_16x16x32_bf16 v[200:203], v[188:191], v[34:37], 0
	v_mul_f32_e32 v91, 0x3fb8aa3b, v168
	v_max3_f32 v66, v66, v91, v99
	v_mul_f32_e32 v91, 0x3fb8aa3b, v174
	s_waitcnt lgkmcnt(0)
	v_mfma_f32_16x16x32_bf16 v[200:203], v[196:199], v[42:45], v[200:203]
	v_mul_f32_e32 v99, 0x3fb8aa3b, v175
	v_max3_f32 v66, v66, v91, v99
	v_mul_f32_e32 v91, 0x3fb8aa3b, v176
	v_mul_f32_e32 v99, 0x3fb8aa3b, v177
	v_max3_f32 v66, v66, v91, v99
	v_mul_f32_e32 v91, 0x3fb8aa3b, v192
	v_mul_f32_e32 v99, 0x3fb8aa3b, v193
	v_max3_f32 v66, v66, v91, v99
	v_mul_f32_e32 v91, 0x3fb8aa3b, v194
	v_mul_f32_e32 v99, 0x3fb8aa3b, v195
	v_max3_f32 v66, v66, v91, v99
	v_mul_f32_e32 v91, 0x3fb8aa3b, v200
	v_mul_f32_e32 v99, 0x3fb8aa3b, v201
	v_max3_f32 v66, v66, v91, v99
	v_mul_f32_e32 v91, 0x3fb8aa3b, v202
	v_mul_f32_e32 v99, 0x3fb8aa3b, v203
	v_max3_f32 v66, v66, v91, v99
	ds_bpermute_b32 v91, v89, v66
	v_mfma_f32_16x16x32_bf16 v[188:191], v[188:191], v[46:49], 0
	v_mul_f32_e32 v99, 0x3fb8aa3b, v161
	s_waitcnt lgkmcnt(0)
	v_max_f32_e32 v91, v91, v91
	v_max_f32_e32 v66, v66, v91
	ds_bpermute_b32 v91, v87, v66
	v_mfma_f32_16x16x32_bf16 v[188:191], v[196:199], v[38:41], v[188:191]
	s_waitcnt lgkmcnt(0)
	v_max3_f32 v66, v95, v66, v91
	v_sub_f32_e32 v91, v95, v66
	v_exp_f32_e32 v180, v91
	v_fma_f32 v91, v166, s81, -v66
	v_exp_f32_e32 v166, v91
	v_fma_f32 v91, v167, s81, -v66
	v_exp_f32_e32 v184, v91
	v_fma_f32 v91, v168, s81, -v66
	v_exp_f32_e32 v168, v91
	v_fma_f32 v91, v169, s81, -v66
	v_exp_f32_e32 v196, v91
	v_fma_f32 v91, v174, s81, -v66
	v_exp_f32_e32 v174, v91
	v_fma_f32 v91, v175, s81, -v66
	v_exp_f32_e32 v198, v91
	v_fma_f32 v91, v176, s81, -v66
	v_exp_f32_e32 v176, v91
	v_fma_f32 v91, v177, s81, -v66
	v_exp_f32_e32 v204, v91
	v_fma_f32 v91, v192, s81, -v66
	v_exp_f32_e32 v192, v91
	v_fma_f32 v91, v193, s81, -v66
	v_exp_f32_e32 v206, v91
	v_fma_f32 v91, v194, s81, -v66
	v_exp_f32_e32 v194, v91
	v_fma_f32 v91, v195, s81, -v66
	v_exp_f32_e32 v208, v91
	v_fma_f32 v91, v200, s81, -v66
	v_exp_f32_e32 v200, v91
	v_fma_f32 v91, v201, s81, -v66
	v_exp_f32_e32 v210, v91
	v_fma_f32 v91, v202, s81, -v66
	v_exp_f32_e32 v202, v91
	v_fma_f32 v91, v203, s81, -v66
	v_exp_f32_e32 v212, v91
	v_mul_f32_e32 v91, 0x3fb8aa3b, v158
	v_mul_f32_e32 v95, 0x3fb8aa3b, v159
	v_max3_f32 v91, v91, s97, v95
	v_mul_f32_e32 v95, 0x3fb8aa3b, v160
	v_max3_f32 v91, v91, v95, v99
	v_mul_f32_e32 v95, 0x3fb8aa3b, v162
	v_mul_f32_e32 v99, 0x3fb8aa3b, v163
	v_max3_f32 v91, v91, v95, v99
	v_mul_f32_e32 v95, 0x3fb8aa3b, v164
	v_mul_f32_e32 v99, 0x3fb8aa3b, v165
	v_max3_f32 v91, v91, v95, v99
	v_mul_f32_e32 v95, 0x3fb8aa3b, v170
	v_mul_f32_e32 v99, 0x3fb8aa3b, v171
	v_max3_f32 v91, v91, v95, v99
	v_mul_f32_e32 v95, 0x3fb8aa3b, v172
	v_mul_f32_e32 v99, 0x3fb8aa3b, v173
	v_max3_f32 v91, v91, v95, v99
	v_mul_f32_e32 v95, 0x3fb8aa3b, v188
	v_mul_f32_e32 v99, 0x3fb8aa3b, v189
	v_max3_f32 v91, v91, v95, v99
	v_mul_f32_e32 v95, 0x3fb8aa3b, v190
	v_mul_f32_e32 v99, 0x3fb8aa3b, v191
	v_max3_f32 v91, v91, v95, v99
	ds_bpermute_b32 v95, v89, v91
	s_waitcnt lgkmcnt(0)
	v_max_f32_e32 v95, v95, v95
	v_max_f32_e32 v91, v91, v95
	ds_bpermute_b32 v95, v87, v91
	s_waitcnt lgkmcnt(0)
	v_max3_f32 v91, v93, v91, v95
	v_sub_f32_e32 v93, v93, v91
	v_exp_f32_e32 v181, v93
	v_fma_f32 v93, v158, s81, -v91
	v_exp_f32_e32 v167, v93
	v_fma_f32 v93, v159, s81, -v91
	v_exp_f32_e32 v185, v93
	v_fma_f32 v93, v160, s81, -v91
	v_exp_f32_e32 v169, v93
	v_fma_f32 v93, v161, s81, -v91
	v_exp_f32_e32 v197, v93
	v_fma_f32 v93, v162, s81, -v91
	v_exp_f32_e32 v175, v93
	v_fma_f32 v93, v163, s81, -v91
	v_exp_f32_e32 v199, v93
	v_fma_f32 v93, v164, s81, -v91
	v_exp_f32_e32 v177, v93
	v_fma_f32 v93, v165, s81, -v91
	v_exp_f32_e32 v205, v93
	v_fma_f32 v93, v170, s81, -v91
	v_exp_f32_e32 v193, v93
	v_fma_f32 v93, v171, s81, -v91
	v_exp_f32_e32 v207, v93
	v_fma_f32 v93, v172, s81, -v91
	v_exp_f32_e32 v195, v93
	v_fma_f32 v93, v173, s81, -v91
	v_pk_add_f32 v[162:163], v[166:167], 0 op_sel_hi:[1,0]
	v_exp_f32_e32 v209, v93
	v_fma_f32 v93, v188, s81, -v91
	v_pk_add_f32 v[162:163], v[184:185], v[162:163]
	v_exp_f32_e32 v201, v93
	v_fma_f32 v93, v189, s81, -v91
	v_pk_add_f32 v[162:163], v[168:169], v[162:163]
	v_exp_f32_e32 v211, v93
	v_fma_f32 v93, v190, s81, -v91
	v_pk_add_f32 v[162:163], v[196:197], v[162:163]
	v_exp_f32_e32 v203, v93
	v_fma_f32 v93, v191, s81, -v91
	v_pk_add_f32 v[162:163], v[174:175], v[162:163]
	v_exp_f32_e32 v213, v93
	v_add_u32_e32 v93, v97, v68
	v_cvt_pk_bf16_f32 v158, v166, v184
	v_pk_add_f32 v[214:215], v[198:199], v[162:163]
	v_mov_b32_e32 v166, v181
	v_add_u32_e32 v95, 0x2000, v93
	v_cvt_pk_bf16_f32 v159, v168, v196
	v_cvt_pk_bf16_f32 v160, v174, v198
	v_cvt_pk_bf16_f32 v161, v176, v204
	v_pk_add_f32 v[170:171], v[176:177], v[214:215]
	v_pk_mul_f32 v[8:9], v[8:9], v[166:167] op_sel_hi:[1,0]
	v_pk_mul_f32 v[6:7], v[6:7], v[166:167] op_sel_hi:[1,0]
	v_pk_mul_f32 v[4:5], v[4:5], v[166:167] op_sel_hi:[1,0]
	v_pk_mul_f32 v[2:3], v[2:3], v[166:167] op_sel_hi:[1,0]
	v_pk_mul_f32 v[12:13], v[12:13], v[166:167] op_sel_hi:[1,0]
	v_pk_mul_f32 v[10:11], v[10:11], v[166:167] op_sel_hi:[1,0]
	v_pk_mul_f32 v[16:17], v[16:17], v[166:167] op_sel_hi:[1,0]
	v_pk_mul_f32 v[14:15], v[14:15], v[166:167] op_sel_hi:[1,0]
	v_cvt_pk_bf16_f32 v166, v167, v185
	v_cvt_pk_bf16_f32 v167, v169, v197
	v_cvt_pk_bf16_f32 v168, v175, v199
	v_cvt_pk_bf16_f32 v169, v177, v205
	ds_read2_b64 v[174:177], v95 offset0:128 offset1:132
	v_pk_mul_f32 v[28:29], v[28:29], v[180:181] op_sel_hi:[1,0]
	v_pk_mul_f32 v[26:27], v[26:27], v[180:181] op_sel_hi:[1,0]
	v_pk_add_f32 v[170:171], v[204:205], v[170:171]
	s_waitcnt lgkmcnt(0)
	v_mfma_f32_16x16x32_bf16 v[6:9], v[174:177], v[166:169], v[6:9]
	v_add_f32_e64 v170, v192, v170
	v_add_f32_e64 v171, v193, v171
	v_cvt_pk_bf16_f32 v162, v192, v206
	v_pk_add_f32 v[170:171], v[206:207], v[170:171]
	v_mfma_f32_16x16x32_bf16 v[26:29], v[174:177], v[158:161], v[26:29]
	ds_read2_b64 v[174:177], v95 offset0:136 offset1:140
	v_pk_add_f32 v[170:171], v[194:195], v[170:171]
	v_cvt_pk_bf16_f32 v163, v194, v208
	v_pk_add_f32 v[170:171], v[208:209], v[170:171]
	v_cvt_pk_bf16_f32 v164, v200, v210
	v_pk_add_f32 v[170:171], v[200:201], v[170:171]
	v_cvt_pk_bf16_f32 v165, v202, v212
	v_pk_add_f32 v[170:171], v[210:211], v[170:171]
	v_cvt_pk_bf16_f32 v172, v201, v211
	v_pk_add_f32 v[170:171], v[202:203], v[170:171]
	v_cvt_pk_bf16_f32 v173, v203, v213
	v_pk_add_f32 v[170:171], v[212:213], v[170:171]
	v_add_u32_e32 v95, 0x2800, v93
	v_pk_fma_f32 v[112:113], v[112:113], v[180:181], v[170:171]
	v_cvt_pk_bf16_f32 v170, v193, v207
	v_cvt_pk_bf16_f32 v171, v195, v209
	s_waitcnt lgkmcnt(0)
	v_mfma_f32_16x16x32_bf16 v[26:29], v[174:177], v[162:165], v[26:29]
	v_mul_f32_e64 v20, v20, v180
	v_mul_f32_e64 v21, v21, v180
	v_pk_mul_f32 v[18:19], v[18:19], v[180:181] op_sel_hi:[1,0]
	v_pk_mul_f32 v[24:25], v[24:25], v[180:181] op_sel_hi:[1,0]
	v_mfma_f32_16x16x32_bf16 v[6:9], v[174:177], v[170:173], v[6:9]
	ds_read2_b64 v[174:177], v95 offset0:160 offset1:164
	v_pk_mul_f32 v[22:23], v[22:23], v[180:181] op_sel_hi:[1,0]
	v_pk_mul_f32 v[32:33], v[32:33], v[180:181] op_sel_hi:[1,0]
	s_waitcnt lgkmcnt(0)
	v_mfma_f32_16x16x32_bf16 v[18:21], v[174:177], v[158:161], v[18:21]
	v_mul_f32_e64 v30, v30, v180
	v_mul_f32_e64 v31, v31, v180
	v_mfma_f32_16x16x32_bf16 v[2:5], v[174:177], v[166:169], v[2:5]
	ds_read2_b64 v[174:177], v95 offset0:168 offset1:172
	v_add_u32_e32 v95, 0x3000, v93
	v_add_u32_e32 v93, 0x3800, v93
	s_waitcnt lgkmcnt(0)
	v_mfma_f32_16x16x32_bf16 v[18:21], v[174:177], v[162:165], v[18:21]
	v_mfma_f32_16x16x32_bf16 v[2:5], v[174:177], v[170:173], v[2:5]
	ds_read2_b64 v[174:177], v95 offset0:192 offset1:196
	s_waitcnt lgkmcnt(0)
	v_mfma_f32_16x16x32_bf16 v[22:25], v[174:177], v[158:161], v[22:25]
	v_mfma_f32_16x16x32_bf16 v[10:13], v[174:177], v[166:169], v[10:13]
	ds_read2_b64 v[174:177], v95 offset0:200 offset1:204
	v_mov_b32_e32 v95, v66
	s_waitcnt lgkmcnt(0)
	v_mfma_f32_16x16x32_bf16 v[22:25], v[174:177], v[162:165], v[22:25]
	v_mfma_f32_16x16x32_bf16 v[10:13], v[174:177], v[170:173], v[10:13]
	ds_read2_b64 v[174:177], v93 offset0:224 offset1:228
	s_waitcnt lgkmcnt(0)
	v_mfma_f32_16x16x32_bf16 v[30:33], v[174:177], v[158:161], v[30:33]
	ds_read2_b64 v[158:161], v93 offset0:232 offset1:236
	v_mov_b32_e32 v93, v91
	s_waitcnt lgkmcnt(0)
	v_mfma_f32_16x16x32_bf16 v[14:17], v[174:177], v[166:169], v[14:17]
	s_barrier
	v_mfma_f32_16x16x32_bf16 v[30:33], v[158:161], v[162:165], v[30:33]
	v_mfma_f32_16x16x32_bf16 v[14:17], v[158:161], v[170:173], v[14:17]
.Lattpf_a0_b:
	s_add_i32 s20, s21, 1
	s_bitcmp1_b32 s20, 0
	s_cselect_b32 s16, 0x4800, 0
	v_add_u32_e32 v66, s16, v69
	s_min_i32 s16, s20, 21
	s_lshl_b32 s22, s16, 6
	s_waitcnt vmcnt(7)
	ds_write_b128 v66, v[216:219]
	s_waitcnt vmcnt(6)
	ds_write_b128 v66, v[220:223] offset:9216
	s_waitcnt vmcnt(5)
	ds_write_b128 v66, v[224:227] offset:4608
	s_waitcnt vmcnt(4)
	ds_write_b128 v66, v[228:231] offset:13824
	v_add_lshl_u32 v66, s22, v152, 9
	s_lshl_b32 s16, s16, 7
	v_lshl_add_u64 v[224:225], v[116:117], 0, v[66:67]
	v_lshl_add_u64 v[228:229], v[118:119], 0, s[16:17]
	s_bitcmp1_b32 s21, 0
	global_load_dwordx4 v[216:219], v[224:225], off
	global_load_dwordx4 v[220:223], v[228:229], off offset:256
	v_add_co_u32_e32 v224, vcc, s19, v224
	s_cselect_b32 s16, 0x4800, 0
	s_nop 0
	v_addc_co_u32_e32 v225, vcc, 0, v225, vcc
	s_add_i32 s16, s16, 32
	v_add_co_u32_e32 v228, vcc, s96, v228
	v_add_u32_e32 v97, s16, v151
	s_nop 0
	v_addc_co_u32_e32 v229, vcc, 0, v229, vcc
	v_lshl_add_u32 v66, v68, 1, v97
	global_load_dwordx4 v[224:227], v[224:225], off
	s_cmp_lg_u32 s20, 24
	global_load_dwordx4 v[228:231], v[228:229], off offset:256
	ds_read_b128 v[158:161], v66
	ds_read_b128 v[162:165], v66 offset:64
	s_waitcnt lgkmcnt(1)
	v_mfma_f32_16x16x32_bf16 v[166:169], v[158:161], v[34:37], 0
	s_mov_b32 s21, s20
	v_mfma_f32_16x16x32_bf16 v[158:161], v[158:161], v[46:49], 0
	s_waitcnt lgkmcnt(0)
	v_mfma_f32_16x16x32_bf16 v[166:169], v[162:165], v[42:45], v[166:169]
	v_mfma_f32_16x16x32_bf16 v[158:161], v[162:165], v[38:41], v[158:161]
	ds_read_b128 v[162:165], v66 offset:2304
	ds_read_b128 v[170:173], v66 offset:2368
	s_nop 4
	v_mul_f32_e32 v91, 0x3fb8aa3b, v167
	v_mul_f32_e32 v99, 0x3fb8aa3b, v169
	s_waitcnt lgkmcnt(1)
	v_mfma_f32_16x16x32_bf16 v[174:177], v[162:165], v[34:37], 0
	v_mfma_f32_16x16x32_bf16 v[162:165], v[162:165], v[46:49], 0
	s_waitcnt lgkmcnt(0)
	v_mfma_f32_16x16x32_bf16 v[174:177], v[170:173], v[42:45], v[174:177]
	v_mfma_f32_16x16x32_bf16 v[162:165], v[170:173], v[38:41], v[162:165]
	ds_read_b128 v[170:173], v66 offset:4608
	ds_read_b128 v[188:191], v66 offset:4672
	s_waitcnt lgkmcnt(1)
	v_mfma_f32_16x16x32_bf16 v[192:195], v[170:173], v[34:37], 0
	v_mfma_f32_16x16x32_bf16 v[170:173], v[170:173], v[46:49], 0
	s_waitcnt lgkmcnt(0)
	v_mfma_f32_16x16x32_bf16 v[192:195], v[188:191], v[42:45], v[192:195]
	v_mfma_f32_16x16x32_bf16 v[170:173], v[188:191], v[38:41], v[170:173]
	ds_read_b128 v[188:191], v66 offset:6912
	ds_read_b128 v[196:199], v66 offset:6976
	v_mul_f32_e32 v66, 0x3fb8aa3b, v166
	v_max3_f32 v66, v66, s97, v91
	s_waitcnt lgkmcnt(1)
	v_mfma_f32_16x16x32_bf16 v[200:203], v[188:191], v[34:37], 0
	v_mul_f32_e32 v91, 0x3fb8aa3b, v168
	v_max3_f32 v66, v66, v91, v99
	v_mul_f32_e32 v91, 0x3fb8aa3b, v174
	s_waitcnt lgkmcnt(0)
	v_mfma_f32_16x16x32_bf16 v[200:203], v[196:199], v[42:45], v[200:203]
	v_mul_f32_e32 v99, 0x3fb8aa3b, v175
	v_max3_f32 v66, v66, v91, v99
	v_mul_f32_e32 v91, 0x3fb8aa3b, v176
	v_mul_f32_e32 v99, 0x3fb8aa3b, v177
	v_max3_f32 v66, v66, v91, v99
	v_mul_f32_e32 v91, 0x3fb8aa3b, v192
	v_mul_f32_e32 v99, 0x3fb8aa3b, v193
	v_max3_f32 v66, v66, v91, v99
	v_mul_f32_e32 v91, 0x3fb8aa3b, v194
	v_mul_f32_e32 v99, 0x3fb8aa3b, v195
	v_max3_f32 v66, v66, v91, v99
	v_mul_f32_e32 v91, 0x3fb8aa3b, v200
	v_mul_f32_e32 v99, 0x3fb8aa3b, v201
	v_max3_f32 v66, v66, v91, v99
	v_mul_f32_e32 v91, 0x3fb8aa3b, v202
	v_mul_f32_e32 v99, 0x3fb8aa3b, v203
	v_max3_f32 v66, v66, v91, v99
	ds_bpermute_b32 v91, v89, v66
	v_mfma_f32_16x16x32_bf16 v[188:191], v[188:191], v[46:49], 0
	v_mul_f32_e32 v99, 0x3fb8aa3b, v161
	s_waitcnt lgkmcnt(0)
	v_max_f32_e32 v91, v91, v91
	v_max_f32_e32 v66, v66, v91
	ds_bpermute_b32 v91, v87, v66
	v_mfma_f32_16x16x32_bf16 v[188:191], v[196:199], v[38:41], v[188:191]
	s_waitcnt lgkmcnt(0)
	v_max3_f32 v66, v95, v66, v91
	v_sub_f32_e32 v91, v95, v66
	v_exp_f32_e32 v180, v91
	v_fma_f32 v91, v166, s81, -v66
	v_exp_f32_e32 v166, v91
	v_fma_f32 v91, v167, s81, -v66
	v_exp_f32_e32 v184, v91
	v_fma_f32 v91, v168, s81, -v66
	v_exp_f32_e32 v168, v91
	v_fma_f32 v91, v169, s81, -v66
	v_exp_f32_e32 v196, v91
	v_fma_f32 v91, v174, s81, -v66
	v_exp_f32_e32 v174, v91
	v_fma_f32 v91, v175, s81, -v66
	v_exp_f32_e32 v198, v91
	v_fma_f32 v91, v176, s81, -v66
	v_exp_f32_e32 v176, v91
	v_fma_f32 v91, v177, s81, -v66
	v_exp_f32_e32 v204, v91
	v_fma_f32 v91, v192, s81, -v66
	v_exp_f32_e32 v192, v91
	v_fma_f32 v91, v193, s81, -v66
	v_exp_f32_e32 v206, v91
	v_fma_f32 v91, v194, s81, -v66
	v_exp_f32_e32 v194, v91
	v_fma_f32 v91, v195, s81, -v66
	v_exp_f32_e32 v208, v91
	v_fma_f32 v91, v200, s81, -v66
	v_exp_f32_e32 v200, v91
	v_fma_f32 v91, v201, s81, -v66
	v_exp_f32_e32 v210, v91
	v_fma_f32 v91, v202, s81, -v66
	v_exp_f32_e32 v202, v91
	v_fma_f32 v91, v203, s81, -v66
	v_exp_f32_e32 v212, v91
	v_mul_f32_e32 v91, 0x3fb8aa3b, v158
	v_mul_f32_e32 v95, 0x3fb8aa3b, v159
	v_max3_f32 v91, v91, s97, v95
	v_mul_f32_e32 v95, 0x3fb8aa3b, v160
	v_max3_f32 v91, v91, v95, v99
	v_mul_f32_e32 v95, 0x3fb8aa3b, v162
	v_mul_f32_e32 v99, 0x3fb8aa3b, v163
	v_max3_f32 v91, v91, v95, v99
	v_mul_f32_e32 v95, 0x3fb8aa3b, v164
	v_mul_f32_e32 v99, 0x3fb8aa3b, v165
	v_max3_f32 v91, v91, v95, v99
	v_mul_f32_e32 v95, 0x3fb8aa3b, v170
	v_mul_f32_e32 v99, 0x3fb8aa3b, v171
	v_max3_f32 v91, v91, v95, v99
	v_mul_f32_e32 v95, 0x3fb8aa3b, v172
	v_mul_f32_e32 v99, 0x3fb8aa3b, v173
	v_max3_f32 v91, v91, v95, v99
	v_mul_f32_e32 v95, 0x3fb8aa3b, v188
	v_mul_f32_e32 v99, 0x3fb8aa3b, v189
	v_max3_f32 v91, v91, v95, v99
	v_mul_f32_e32 v95, 0x3fb8aa3b, v190
	v_mul_f32_e32 v99, 0x3fb8aa3b, v191
	v_max3_f32 v91, v91, v95, v99
	ds_bpermute_b32 v95, v89, v91
	s_waitcnt lgkmcnt(0)
	v_max_f32_e32 v95, v95, v95
	v_max_f32_e32 v91, v91, v95
	ds_bpermute_b32 v95, v87, v91
	s_waitcnt lgkmcnt(0)
	v_max3_f32 v91, v93, v91, v95
	v_sub_f32_e32 v93, v93, v91
	v_exp_f32_e32 v181, v93
	v_fma_f32 v93, v158, s81, -v91
	v_exp_f32_e32 v167, v93
	v_fma_f32 v93, v159, s81, -v91
	v_exp_f32_e32 v185, v93
	v_fma_f32 v93, v160, s81, -v91
	v_exp_f32_e32 v169, v93
	v_fma_f32 v93, v161, s81, -v91
	v_exp_f32_e32 v197, v93
	v_fma_f32 v93, v162, s81, -v91
	v_exp_f32_e32 v175, v93
	v_fma_f32 v93, v163, s81, -v91
	v_exp_f32_e32 v199, v93
	v_fma_f32 v93, v164, s81, -v91
	v_exp_f32_e32 v177, v93
	v_fma_f32 v93, v165, s81, -v91
	v_exp_f32_e32 v205, v93
	v_fma_f32 v93, v170, s81, -v91
	v_exp_f32_e32 v193, v93
	v_fma_f32 v93, v171, s81, -v91
	v_exp_f32_e32 v207, v93
	v_fma_f32 v93, v172, s81, -v91
	v_exp_f32_e32 v195, v93
	v_fma_f32 v93, v173, s81, -v91
	v_pk_add_f32 v[162:163], v[166:167], 0 op_sel_hi:[1,0]
	v_exp_f32_e32 v209, v93
	v_fma_f32 v93, v188, s81, -v91
	v_pk_add_f32 v[162:163], v[184:185], v[162:163]
	v_exp_f32_e32 v201, v93
	v_fma_f32 v93, v189, s81, -v91
	v_pk_add_f32 v[162:163], v[168:169], v[162:163]
	v_exp_f32_e32 v211, v93
	v_fma_f32 v93, v190, s81, -v91
	v_pk_add_f32 v[162:163], v[196:197], v[162:163]
	v_exp_f32_e32 v203, v93
	v_fma_f32 v93, v191, s81, -v91
	v_pk_add_f32 v[162:163], v[174:175], v[162:163]
	v_exp_f32_e32 v213, v93
	v_add_u32_e32 v93, v97, v68
	v_cvt_pk_bf16_f32 v158, v166, v184
	v_pk_add_f32 v[214:215], v[198:199], v[162:163]
	v_mov_b32_e32 v166, v181
	v_add_u32_e32 v95, 0x2000, v93
	v_cvt_pk_bf16_f32 v159, v168, v196
	v_cvt_pk_bf16_f32 v160, v174, v198
	v_cvt_pk_bf16_f32 v161, v176, v204
	v_pk_add_f32 v[170:171], v[176:177], v[214:215]
	v_pk_mul_f32 v[8:9], v[8:9], v[166:167] op_sel_hi:[1,0]
	v_pk_mul_f32 v[6:7], v[6:7], v[166:167] op_sel_hi:[1,0]
	v_pk_mul_f32 v[4:5], v[4:5], v[166:167] op_sel_hi:[1,0]
	v_pk_mul_f32 v[2:3], v[2:3], v[166:167] op_sel_hi:[1,0]
	v_pk_mul_f32 v[12:13], v[12:13], v[166:167] op_sel_hi:[1,0]
	v_pk_mul_f32 v[10:11], v[10:11], v[166:167] op_sel_hi:[1,0]
	v_pk_mul_f32 v[16:17], v[16:17], v[166:167] op_sel_hi:[1,0]
	v_pk_mul_f32 v[14:15], v[14:15], v[166:167] op_sel_hi:[1,0]
	v_cvt_pk_bf16_f32 v166, v167, v185
	v_cvt_pk_bf16_f32 v167, v169, v197
	v_cvt_pk_bf16_f32 v168, v175, v199
	v_cvt_pk_bf16_f32 v169, v177, v205
	ds_read2_b64 v[174:177], v95 offset0:128 offset1:132
	v_pk_mul_f32 v[28:29], v[28:29], v[180:181] op_sel_hi:[1,0]
	v_pk_mul_f32 v[26:27], v[26:27], v[180:181] op_sel_hi:[1,0]
	v_pk_add_f32 v[170:171], v[204:205], v[170:171]
	s_waitcnt lgkmcnt(0)
	v_mfma_f32_16x16x32_bf16 v[6:9], v[174:177], v[166:169], v[6:9]
	v_add_f32_e64 v170, v192, v170
	v_add_f32_e64 v171, v193, v171
	v_cvt_pk_bf16_f32 v162, v192, v206
	v_pk_add_f32 v[170:171], v[206:207], v[170:171]
	v_mfma_f32_16x16x32_bf16 v[26:29], v[174:177], v[158:161], v[26:29]
	ds_read2_b64 v[174:177], v95 offset0:136 offset1:140
	v_pk_add_f32 v[170:171], v[194:195], v[170:171]
	v_cvt_pk_bf16_f32 v163, v194, v208
	v_pk_add_f32 v[170:171], v[208:209], v[170:171]
	v_cvt_pk_bf16_f32 v164, v200, v210
	v_pk_add_f32 v[170:171], v[200:201], v[170:171]
	v_cvt_pk_bf16_f32 v165, v202, v212
	v_pk_add_f32 v[170:171], v[210:211], v[170:171]
	v_cvt_pk_bf16_f32 v172, v201, v211
	v_pk_add_f32 v[170:171], v[202:203], v[170:171]
	v_cvt_pk_bf16_f32 v173, v203, v213
	v_pk_add_f32 v[170:171], v[212:213], v[170:171]
	v_add_u32_e32 v95, 0x2800, v93
	v_pk_fma_f32 v[112:113], v[112:113], v[180:181], v[170:171]
	v_cvt_pk_bf16_f32 v170, v193, v207
	v_cvt_pk_bf16_f32 v171, v195, v209
	s_waitcnt lgkmcnt(0)
	v_mfma_f32_16x16x32_bf16 v[26:29], v[174:177], v[162:165], v[26:29]
	v_mul_f32_e64 v20, v20, v180
	v_mul_f32_e64 v21, v21, v180
	v_pk_mul_f32 v[18:19], v[18:19], v[180:181] op_sel_hi:[1,0]
	v_pk_mul_f32 v[24:25], v[24:25], v[180:181] op_sel_hi:[1,0]
	v_mfma_f32_16x16x32_bf16 v[6:9], v[174:177], v[170:173], v[6:9]
	ds_read2_b64 v[174:177], v95 offset0:160 offset1:164
	v_pk_mul_f32 v[22:23], v[22:23], v[180:181] op_sel_hi:[1,0]
	v_pk_mul_f32 v[32:33], v[32:33], v[180:181] op_sel_hi:[1,0]
	s_waitcnt lgkmcnt(0)
	v_mfma_f32_16x16x32_bf16 v[18:21], v[174:177], v[158:161], v[18:21]
	v_mul_f32_e64 v30, v30, v180
	v_mul_f32_e64 v31, v31, v180
	v_mfma_f32_16x16x32_bf16 v[2:5], v[174:177], v[166:169], v[2:5]
	ds_read2_b64 v[174:177], v95 offset0:168 offset1:172
	v_add_u32_e32 v95, 0x3000, v93
	v_add_u32_e32 v93, 0x3800, v93
	s_waitcnt lgkmcnt(0)
	v_mfma_f32_16x16x32_bf16 v[18:21], v[174:177], v[162:165], v[18:21]
	v_mfma_f32_16x16x32_bf16 v[2:5], v[174:177], v[170:173], v[2:5]
	ds_read2_b64 v[174:177], v95 offset0:192 offset1:196
	s_waitcnt lgkmcnt(0)
	v_mfma_f32_16x16x32_bf16 v[22:25], v[174:177], v[158:161], v[22:25]
	v_mfma_f32_16x16x32_bf16 v[10:13], v[174:177], v[166:169], v[10:13]
	ds_read2_b64 v[174:177], v95 offset0:200 offset1:204
	v_mov_b32_e32 v95, v66
	s_waitcnt lgkmcnt(0)
	v_mfma_f32_16x16x32_bf16 v[22:25], v[174:177], v[162:165], v[22:25]
	v_mfma_f32_16x16x32_bf16 v[10:13], v[174:177], v[170:173], v[10:13]
	ds_read2_b64 v[174:177], v93 offset0:224 offset1:228
	s_waitcnt lgkmcnt(0)
	v_mfma_f32_16x16x32_bf16 v[30:33], v[174:177], v[158:161], v[30:33]
	ds_read2_b64 v[158:161], v93 offset0:232 offset1:236
	v_mov_b32_e32 v93, v91
	s_waitcnt lgkmcnt(0)
	v_mfma_f32_16x16x32_bf16 v[14:17], v[174:177], v[166:169], v[14:17]
	s_barrier
	v_mfma_f32_16x16x32_bf16 v[30:33], v[158:161], v[162:165], v[30:33]
	v_mfma_f32_16x16x32_bf16 v[14:17], v[158:161], v[170:173], v[14:17]
	s_cbranch_scc1 .LBB0_348
	s_waitcnt vmcnt(0)
	ds_bpermute_b32 v37, v89, v112
	v_or_b32_e32 v36, v114, v140
	s_lshl_b32 s16, s9, 1
	v_lshl_add_u64 v[34:35], v[84:85], 0, s[16:17]
	s_waitcnt lgkmcnt(0)
	v_add_f32_e32 v37, v112, v37
	ds_bpermute_b32 v38, v87, v37
	s_waitcnt lgkmcnt(0)
	v_add_f32_e32 v37, v37, v38
	v_div_scale_f32 v38, s[20:21], v37, v37, 1.0
	v_rcp_f32_e32 v39, v38
	s_nop 0
	v_fma_f32 v40, -v38, v39, 1.0
	v_fmac_f32_e32 v39, v40, v39
	v_div_scale_f32 v40, vcc, 1.0, v37, 1.0
	v_mul_f32_e32 v41, v40, v39
	v_fma_f32 v42, -v38, v41, v40
	v_fmac_f32_e32 v41, v42, v39
	v_fma_f32 v38, -v38, v41, v40
	v_div_fmas_f32 v38, v38, v39, v41
	v_div_fixup_f32 v38, v38, v37, 1.0
	v_ashrrev_i32_e32 v37, 31, v36
	v_lshlrev_b64 v[40:41], 11, v[36:37]
	v_pk_mul_f32 v[18:19], v[18:19], v[38:39] op_sel_hi:[1,0]
	v_pk_mul_f32 v[20:21], v[20:21], v[38:39] op_sel_hi:[1,0]
	v_lshl_add_u64 v[40:41], v[34:35], 0, v[40:41]
	v_cvt_pk_bf16_f32 v18, v18, v19
	v_cvt_pk_bf16_f32 v19, v20, v21
	global_store_dwordx2 v[40:41], v[18:19], off offset:32
	v_pk_mul_f32 v[18:19], v[22:23], v[38:39] op_sel_hi:[1,0]
	v_pk_mul_f32 v[20:21], v[24:25], v[38:39] op_sel_hi:[1,0]
	v_cvt_pk_bf16_f32 v18, v18, v19
	v_cvt_pk_bf16_f32 v19, v20, v21
	global_store_dwordx2 v[40:41], v[18:19], off offset:64
	v_pk_mul_f32 v[18:19], v[30:31], v[38:39] op_sel_hi:[1,0]
	v_pk_mul_f32 v[20:21], v[32:33], v[38:39] op_sel_hi:[1,0]
	v_cvt_pk_bf16_f32 v18, v18, v19
	v_cvt_pk_bf16_f32 v19, v20, v21
	global_store_dwordx2 v[40:41], v[18:19], off offset:96
	ds_bpermute_b32 v18, v89, v113
	v_pk_mul_f32 v[26:27], v[26:27], v[38:39] op_sel_hi:[1,0]
	v_pk_mul_f32 v[28:29], v[28:29], v[38:39] op_sel_hi:[1,0]
	v_cvt_pk_bf16_f32 v26, v26, v27
	v_cvt_pk_bf16_f32 v27, v28, v29
	s_waitcnt lgkmcnt(0)
	v_add_f32_e32 v18, v113, v18
	ds_bpermute_b32 v19, v87, v18
	global_store_dwordx2 v[40:41], v[26:27], off
	s_waitcnt lgkmcnt(0)
	v_add_f32_e32 v18, v18, v19
	v_div_scale_f32 v19, s[20:21], v18, v18, 1.0
	v_rcp_f32_e32 v20, v19
	s_nop 0
	v_fma_f32 v21, -v19, v20, 1.0
	v_fmac_f32_e32 v20, v21, v20
	v_div_scale_f32 v21, vcc, 1.0, v18, 1.0
	v_mul_f32_e32 v22, v21, v20
	v_fma_f32 v23, -v19, v22, v21
	v_fmac_f32_e32 v22, v23, v20
	v_fma_f32 v19, -v19, v22, v21
	v_div_fmas_f32 v19, v19, v20, v22
	v_or_b32_e32 v20, 16, v36
	v_div_fixup_f32 v18, v19, v18, 1.0
	v_ashrrev_i32_e32 v21, 31, v20
	v_lshlrev_b64 v[20:21], 11, v[20:21]
	v_pk_mul_f32 v[2:3], v[2:3], v[18:19] op_sel_hi:[1,0]
	v_pk_mul_f32 v[4:5], v[4:5], v[18:19] op_sel_hi:[1,0]
	v_lshl_add_u64 v[20:21], v[34:35], 0, v[20:21]
	v_cvt_pk_bf16_f32 v2, v2, v3
	v_cvt_pk_bf16_f32 v3, v4, v5
	global_store_dwordx2 v[20:21], v[2:3], off offset:32
	v_pk_mul_f32 v[2:3], v[10:11], v[18:19] op_sel_hi:[1,0]
	v_pk_mul_f32 v[4:5], v[12:13], v[18:19] op_sel_hi:[1,0]
	v_cvt_pk_bf16_f32 v2, v2, v3
	v_cvt_pk_bf16_f32 v3, v4, v5
	v_pk_mul_f32 v[6:7], v[6:7], v[18:19] op_sel_hi:[1,0]
	v_pk_mul_f32 v[8:9], v[8:9], v[18:19] op_sel_hi:[1,0]
	global_store_dwordx2 v[20:21], v[2:3], off offset:64
	v_pk_mul_f32 v[2:3], v[14:15], v[18:19] op_sel_hi:[1,0]
	v_pk_mul_f32 v[4:5], v[16:17], v[18:19] op_sel_hi:[1,0]
	v_cvt_pk_bf16_f32 v6, v6, v7
	v_cvt_pk_bf16_f32 v7, v8, v9
	v_cvt_pk_bf16_f32 v2, v2, v3
	v_cvt_pk_bf16_f32 v3, v4, v5
	global_store_dwordx2 v[20:21], v[6:7], off
	global_store_dwordx2 v[20:21], v[2:3], off offset:96
	s_branch .LBB0_313

.LBB0_1086:
	s_and_b64 vcc, exec, s[10:11]
	s_cbranch_vccz .LBB0_1053
	s_and_b32 s101, s30, 7
	s_lshr_b32 s100, s30, 3
	s_and_b32 s99, s101, 1
	s_lshl_b32 s99, s99, 1
	s_and_b32 s98, s100, 1
	s_or_b32 s99, s99, s98
	s_lshl_b32 s99, s99, 2
	s_bfe_u32 s98, s100, 0x20001
	s_or_b32 s99, s99, s98
	s_lshl_b32 s99, s99, 3
	s_lshr_b32 s98, s100, 3
	s_or_b32 s99, s99, s98
	s_lshr_b32 s101, s101, 1
	s_lshl_b32 s101, s101, 7
	s_or_b32 s101, s101, s99
	s_ashr_i32 s10, s101, 7
	s_lshl_b32 s15, s10, 10
	s_add_i32 s10, s10, 4
	s_bfe_u32 s14, s101, 0x40003
	s_ashr_i32 s11, s10, 31
	s_mul_i32 s13, s10, 0xc0000
	s_mul_hi_i32 s12, s10, 0xc0000
	s_add_u32 s13, s33, s13
	s_addc_u32 s16, s20, s12
	s_lshl_b32 s12, s101, 1
	s_and_b32 s17, s12, 0xc0
	s_lshl_b32 s12, s17, 1
	s_add_u32 s12, s13, s12
	s_addc_u32 s13, s16, 0
	s_lshl_b64 s[10:11], s[10:11], 8
	s_or_b32 s10, s10, s17
	s_mulk_i32 s11, 0xc00
	s_mul_hi_u32 s16, s10, 0xc00
	s_add_i32 s16, s16, s11
	s_mulk_i32 s10, 0xc00
	s_add_u32 s10, s21, s10
	s_addc_u32 s11, s22, s16
	s_lshl_b32 s16, s101, 7
	s_and_b32 s16, s16, 0x380
	s_or_b32 s15, s15, s16
	v_add_u32_e32 v114, s15, v151
	v_ashrrev_i32_e32 v115, 31, v114
	v_lshlrev_b64 v[2:3], 11, v[114:115]
	v_mov_b32_e32 v107, v67
	v_lshl_add_u64 v[2:3], s[94:95], 0, v[2:3]
	s_lshl_b32 s96, s14, 7
	v_lshl_add_u64 v[4:5], s[10:11], 0, v[106:107]
	v_mov_b32_e32 v109, v67
	v_lshl_add_u64 v[2:3], v[2:3], 0, s[96:97]
	v_lshl_add_u64 v[118:119], v[4:5], 0, v[108:109]
	v_lshlrev_b32_e32 v66, 1, v68
	v_lshl_add_u64 v[116:117], s[12:13], 0, v[106:107]
	v_add_co_u32_e32 v10, vcc, s28, v118
	v_lshl_add_u64 v[2:3], v[2:3], 0, v[66:67]
	v_mov_b32_e32 v105, v67
	v_lshl_add_u64 v[18:19], v[116:117], 0, v[70:71]
	v_lshl_add_u64 v[4:5], v[116:117], 0, v[72:73]
	v_addc_co_u32_e32 v11, vcc, 0, v119, vcc
	v_lshl_add_u64 v[2:3], v[2:3], 0, v[104:105]
	s_mov_b32 s12, 0x8000
	global_load_dwordx4 v[6:9], v[4:5], off
	s_nop 0
	global_load_dwordx4 v[10:13], v[10:11], off
	s_nop 0
	global_load_dwordx4 v[14:17], v[118:119], off
	s_nop 0
	global_load_dwordx4 v[18:21], v[18:19], off
	v_add_co_u32_e32 v4, vcc, s12, v2
	v_mov_b32_e32 v111, v67
	s_nop 0
	v_addc_co_u32_e32 v5, vcc, 0, v3, vcc
	global_load_dwordx4 v[34:37], v[2:3], off
	global_load_dwordx4 v[38:41], v[4:5], off offset:64
	global_load_dwordx4 v[42:45], v[2:3], off offset:64
	global_load_dwordx4 v[46:49], v[4:5], off
	v_lshl_add_u64 v[2:3], v[116:117], 0, v[110:111]
	v_add_co_u32_e32 v4, vcc, s12, v2
	v_lshl_add_u64 v[22:23], s[10:11], 0, v[108:109]
	s_nop 0
	v_addc_co_u32_e32 v5, vcc, 0, v3, vcc
	s_mov_b32 s10, 0xc000
	v_add_co_u32_e32 v2, vcc, s10, v2
	v_lshl_add_u64 v[22:23], v[22:23], 0, v[106:107]
	s_nop 0
	v_addc_co_u32_e32 v3, vcc, 0, v3, vcc
	s_barrier
	global_load_dwordx4 v[50:53], v[4:5], off
	global_load_dwordx4 v[54:57], v[22:23], off offset:128
	v_add_co_u32_e32 v4, vcc, s28, v22
	v_xor_b32_e32 v22, 16, v157
	s_nop 0
	v_addc_co_u32_e32 v5, vcc, 0, v23, vcc
	global_load_dwordx4 v[58:61], v[2:3], off
	global_load_dwordx4 v[62:65], v[4:5], off offset:128
	v_lshlrev_b32_e32 v224, 9, v153
	v_mov_b32_e32 v225, 0
	v_lshl_add_u64 v[224:225], v[116:117], 0, v[224:225]
	v_mov_b32_e32 v228, v118
	v_mov_b32_e32 v229, v119
	global_load_dwordx4 v[216:219], v[224:225], off
	global_load_dwordx4 v[220:223], v[228:229], off offset:256
	v_add_co_u32_e32 v224, vcc, s9, v224
	s_nop 1
	v_addc_co_u32_e32 v225, vcc, 0, v225, vcc
	v_add_co_u32_e32 v228, vcc, s28, v228
	s_nop 1
	v_addc_co_u32_e32 v229, vcc, 0, v229, vcc
	global_load_dwordx4 v[224:227], v[224:225], off
	global_load_dwordx4 v[228:231], v[228:229], off offset:256
	v_and_b32_e32 v3, 64, v157
	v_add_u32_e32 v24, 64, v3
	v_xor_b32_e32 v23, 32, v157
	v_cmp_lt_i32_e32 vcc, v22, v24
	v_mov_b32_e32 v2, 0
	s_mov_b32 s12, 0
	v_cndmask_b32_e32 v22, v157, v22, vcc
	v_cmp_lt_i32_e32 vcc, v23, v24
	v_mov_b32_e32 v95, 0xf149f2ca
	v_mov_b32_e32 v3, v2
	v_cndmask_b32_e32 v23, v157, v23, vcc
	v_mov_b32_e32 v4, v2
	v_mov_b32_e32 v5, v2
	v_lshlrev_b32_e32 v89, 2, v22
	v_lshlrev_b32_e32 v87, 2, v23
	s_lshl_b32 s10, s14, 6
	v_mov_b32_e32 v26, v2
	v_mov_b32_e32 v27, v2
	v_mov_b32_e32 v28, v2
	v_mov_b32_e32 v29, v2
	v_mov_b32_e32 v22, v2
	s_waitcnt vmcnt(15)
	ds_write_b128 v143, v[6:9] offset:4608
	s_waitcnt vmcnt(14)
	ds_write_b128 v143, v[10:13] offset:13824
	s_waitcnt vmcnt(13)
	ds_write_b128 v143, v[14:17] offset:9216
	s_waitcnt vmcnt(12)
	ds_write_b128 v143, v[18:21]
	v_mov_b32_e32 v18, v2
	v_mov_b32_e32 v19, v2
	v_mov_b32_e32 v20, v2
	v_mov_b32_e32 v21, v2
	v_mov_b32_e32 v6, v2
	v_mov_b32_e32 v7, v2
	v_mov_b32_e32 v8, v2
	v_mov_b32_e32 v9, v2
	v_mov_b32_e32 v23, v2
	v_mov_b32_e32 v24, v2
	v_mov_b32_e32 v25, v2
	v_mov_b32_e32 v10, v2
	v_mov_b32_e32 v11, v2
	v_mov_b32_e32 v12, v2
	v_mov_b32_e32 v13, v2
	v_mov_b32_e32 v30, v2
	v_mov_b32_e32 v31, v2
	v_mov_b32_e32 v32, v2
	v_mov_b32_e32 v33, v2
	v_mov_b32_e32 v14, v2
	v_mov_b32_e32 v15, v2
	v_mov_b32_e32 v16, v2
	v_mov_b32_e32 v17, v2
	v_mov_b32_e32 v112, v2
	v_mov_b32_e32 v113, v2
	v_mov_b32_e32 v93, 0xf149f2ca
	s_waitcnt lgkmcnt(0)
	s_barrier
.LBB0_1088:
	s_add_i32 s11, s12, 1
	s_bitcmp1_b32 s11, 0
	s_cselect_b32 s13, 0x4800, 0
	v_add_u32_e32 v66, s13, v69
	s_min_i32 s13, s11, 21
	s_lshl_b32 s14, s13, 6
	s_waitcnt vmcnt(7)
	ds_write_b128 v66, v[50:53]
	s_waitcnt vmcnt(6)
	ds_write_b128 v66, v[54:57] offset:9216
	s_waitcnt vmcnt(5)
	ds_write_b128 v66, v[58:61] offset:4608
	s_waitcnt vmcnt(4)
	ds_write_b128 v66, v[62:65] offset:13824
	v_add_lshl_u32 v66, s14, v153, 9
	s_lshl_b32 s96, s13, 7
	v_lshl_add_u64 v[58:59], v[116:117], 0, v[66:67]
	v_lshl_add_u64 v[62:63], v[118:119], 0, s[96:97]
	s_bitcmp1_b32 s12, 0
	global_load_dwordx4 v[50:53], v[58:59], off
	global_load_dwordx4 v[54:57], v[62:63], off offset:256
	v_add_co_u32_e32 v58, vcc, s9, v58
	s_cselect_b32 s12, 0x4800, 0
	s_nop 0
	v_addc_co_u32_e32 v59, vcc, 0, v59, vcc
	s_add_i32 s12, s12, 32
	v_add_co_u32_e32 v62, vcc, s28, v62
	v_add_u32_e32 v97, s12, v152
	s_nop 0
	v_addc_co_u32_e32 v63, vcc, 0, v63, vcc
	v_lshl_add_u32 v66, v68, 1, v97
	global_load_dwordx4 v[58:61], v[58:59], off
	s_cmp_lg_u32 s11, 24
	global_load_dwordx4 v[62:65], v[62:63], off offset:256
	ds_read_b128 v[158:161], v66
	ds_read_b128 v[162:165], v66 offset:64
	s_waitcnt lgkmcnt(1)
	v_mfma_f32_16x16x32_bf16 v[166:169], v[158:161], v[34:37], 0
	s_mov_b32 s12, s11
	v_mfma_f32_16x16x32_bf16 v[158:161], v[158:161], v[46:49], 0
	s_waitcnt lgkmcnt(0)
	v_mfma_f32_16x16x32_bf16 v[166:169], v[162:165], v[42:45], v[166:169]
	v_mfma_f32_16x16x32_bf16 v[158:161], v[162:165], v[38:41], v[158:161]
	ds_read_b128 v[162:165], v66 offset:2304
	ds_read_b128 v[170:173], v66 offset:2368
	s_nop 4
	v_mul_f32_e32 v91, 0x3fb8aa3b, v167
	v_mul_f32_e32 v99, 0x3fb8aa3b, v169
	s_waitcnt lgkmcnt(1)
	v_mfma_f32_16x16x32_bf16 v[174:177], v[162:165], v[34:37], 0
	v_mfma_f32_16x16x32_bf16 v[162:165], v[162:165], v[46:49], 0
	s_waitcnt lgkmcnt(0)
	v_mfma_f32_16x16x32_bf16 v[174:177], v[170:173], v[42:45], v[174:177]
	v_mfma_f32_16x16x32_bf16 v[162:165], v[170:173], v[38:41], v[162:165]
	ds_read_b128 v[170:173], v66 offset:4608
	ds_read_b128 v[178:181], v66 offset:4672
	s_waitcnt lgkmcnt(1)
	v_mfma_f32_16x16x32_bf16 v[182:185], v[170:173], v[34:37], 0
	v_mfma_f32_16x16x32_bf16 v[170:173], v[170:173], v[46:49], 0
	s_waitcnt lgkmcnt(0)
	v_mfma_f32_16x16x32_bf16 v[182:185], v[178:181], v[42:45], v[182:185]
	v_mfma_f32_16x16x32_bf16 v[170:173], v[178:181], v[38:41], v[170:173]
	ds_read_b128 v[178:181], v66 offset:6912
	ds_read_b128 v[186:189], v66 offset:6976
	v_mul_f32_e32 v66, 0x3fb8aa3b, v166
	v_max3_f32 v66, v66, s29, v91
	s_waitcnt lgkmcnt(1)
	v_mfma_f32_16x16x32_bf16 v[190:193], v[178:181], v[34:37], 0
	v_mul_f32_e32 v91, 0x3fb8aa3b, v168
	v_max3_f32 v66, v66, v91, v99
	v_mul_f32_e32 v91, 0x3fb8aa3b, v174
	s_waitcnt lgkmcnt(0)
	v_mfma_f32_16x16x32_bf16 v[190:193], v[186:189], v[42:45], v[190:193]
	v_mul_f32_e32 v99, 0x3fb8aa3b, v175
	v_max3_f32 v66, v66, v91, v99
	v_mul_f32_e32 v91, 0x3fb8aa3b, v176
	v_mul_f32_e32 v99, 0x3fb8aa3b, v177
	v_max3_f32 v66, v66, v91, v99
	v_mul_f32_e32 v91, 0x3fb8aa3b, v182
	v_mul_f32_e32 v99, 0x3fb8aa3b, v183
	v_max3_f32 v66, v66, v91, v99
	v_mul_f32_e32 v91, 0x3fb8aa3b, v184
	v_mul_f32_e32 v99, 0x3fb8aa3b, v185
	v_max3_f32 v66, v66, v91, v99
	v_mul_f32_e32 v91, 0x3fb8aa3b, v190
	v_mul_f32_e32 v99, 0x3fb8aa3b, v191
	v_max3_f32 v66, v66, v91, v99
	v_mul_f32_e32 v91, 0x3fb8aa3b, v192
	v_mul_f32_e32 v99, 0x3fb8aa3b, v193
	v_max3_f32 v66, v66, v91, v99
	ds_bpermute_b32 v91, v89, v66
	v_mfma_f32_16x16x32_bf16 v[178:181], v[178:181], v[46:49], 0
	v_mul_f32_e32 v99, 0x3fb8aa3b, v161
	s_waitcnt lgkmcnt(0)
	v_max_f32_e32 v91, v91, v91
	v_max_f32_e32 v66, v66, v91
	ds_bpermute_b32 v91, v87, v66
	v_mfma_f32_16x16x32_bf16 v[178:181], v[186:189], v[38:41], v[178:181]
	s_waitcnt lgkmcnt(0)
	v_max3_f32 v66, v95, v66, v91
	v_sub_f32_e32 v91, v95, v66
	v_exp_f32_e32 v186, v91
	v_fma_f32 v91, v166, s27, -v66
	v_exp_f32_e32 v166, v91
	v_fma_f32 v91, v167, s27, -v66
	v_exp_f32_e32 v188, v91
	v_fma_f32 v91, v168, s27, -v66
	v_exp_f32_e32 v168, v91
	v_fma_f32 v91, v169, s27, -v66
	v_exp_f32_e32 v194, v91
	v_fma_f32 v91, v174, s27, -v66
	v_exp_f32_e32 v174, v91
	v_fma_f32 v91, v175, s27, -v66
	v_exp_f32_e32 v196, v91
	v_fma_f32 v91, v176, s27, -v66
	v_exp_f32_e32 v176, v91
	v_fma_f32 v91, v177, s27, -v66
	v_exp_f32_e32 v198, v91
	v_fma_f32 v91, v182, s27, -v66
	v_exp_f32_e32 v182, v91
	v_fma_f32 v91, v183, s27, -v66
	v_exp_f32_e32 v200, v91
	v_fma_f32 v91, v184, s27, -v66
	v_exp_f32_e32 v184, v91
	v_fma_f32 v91, v185, s27, -v66
	v_exp_f32_e32 v202, v91
	v_fma_f32 v91, v190, s27, -v66
	v_exp_f32_e32 v190, v91
	v_fma_f32 v91, v191, s27, -v66
	v_exp_f32_e32 v204, v91
	v_fma_f32 v91, v192, s27, -v66
	v_exp_f32_e32 v192, v91
	v_fma_f32 v91, v193, s27, -v66
	v_exp_f32_e32 v206, v91
	v_mul_f32_e32 v91, 0x3fb8aa3b, v158
	v_mul_f32_e32 v95, 0x3fb8aa3b, v159
	v_max3_f32 v91, v91, s29, v95
	v_mul_f32_e32 v95, 0x3fb8aa3b, v160
	v_max3_f32 v91, v91, v95, v99
	v_mul_f32_e32 v95, 0x3fb8aa3b, v162
	v_mul_f32_e32 v99, 0x3fb8aa3b, v163
	v_max3_f32 v91, v91, v95, v99
	v_mul_f32_e32 v95, 0x3fb8aa3b, v164
	v_mul_f32_e32 v99, 0x3fb8aa3b, v165
	v_max3_f32 v91, v91, v95, v99
	v_mul_f32_e32 v95, 0x3fb8aa3b, v170
	v_mul_f32_e32 v99, 0x3fb8aa3b, v171
	v_max3_f32 v91, v91, v95, v99
	v_mul_f32_e32 v95, 0x3fb8aa3b, v172
	v_mul_f32_e32 v99, 0x3fb8aa3b, v173
	v_max3_f32 v91, v91, v95, v99
	v_mul_f32_e32 v95, 0x3fb8aa3b, v178
	v_mul_f32_e32 v99, 0x3fb8aa3b, v179
	v_max3_f32 v91, v91, v95, v99
	v_mul_f32_e32 v95, 0x3fb8aa3b, v180
	v_mul_f32_e32 v99, 0x3fb8aa3b, v181
	v_max3_f32 v91, v91, v95, v99
	ds_bpermute_b32 v95, v89, v91
	s_waitcnt lgkmcnt(0)
	v_max_f32_e32 v95, v95, v95
	v_max_f32_e32 v91, v91, v95
	ds_bpermute_b32 v95, v87, v91
	s_waitcnt lgkmcnt(0)
	v_max3_f32 v91, v93, v91, v95
	v_sub_f32_e32 v93, v93, v91
	v_exp_f32_e32 v187, v93
	v_fma_f32 v93, v158, s27, -v91
	v_exp_f32_e32 v167, v93
	v_fma_f32 v93, v159, s27, -v91
	v_exp_f32_e32 v189, v93
	v_fma_f32 v93, v160, s27, -v91
	v_exp_f32_e32 v169, v93
	v_fma_f32 v93, v161, s27, -v91
	v_exp_f32_e32 v195, v93
	v_fma_f32 v93, v162, s27, -v91
	v_exp_f32_e32 v175, v93
	v_fma_f32 v93, v163, s27, -v91
	v_exp_f32_e32 v197, v93
	v_fma_f32 v93, v164, s27, -v91
	v_exp_f32_e32 v177, v93
	v_fma_f32 v93, v165, s27, -v91
	v_exp_f32_e32 v199, v93
	v_fma_f32 v93, v170, s27, -v91
	v_exp_f32_e32 v183, v93
	v_fma_f32 v93, v171, s27, -v91
	v_exp_f32_e32 v201, v93
	v_fma_f32 v93, v172, s27, -v91
	v_exp_f32_e32 v185, v93
	v_fma_f32 v93, v173, s27, -v91
	v_pk_add_f32 v[162:163], v[166:167], 0 op_sel_hi:[1,0]
	v_exp_f32_e32 v203, v93
	v_fma_f32 v93, v178, s27, -v91
	v_pk_add_f32 v[162:163], v[188:189], v[162:163]
	v_exp_f32_e32 v191, v93
	v_fma_f32 v93, v179, s27, -v91
	v_pk_add_f32 v[162:163], v[168:169], v[162:163]
	v_exp_f32_e32 v205, v93
	v_fma_f32 v93, v180, s27, -v91
	v_pk_add_f32 v[162:163], v[194:195], v[162:163]
	v_exp_f32_e32 v193, v93
	v_fma_f32 v93, v181, s27, -v91
	v_pk_add_f32 v[162:163], v[174:175], v[162:163]
	v_exp_f32_e32 v207, v93
	v_add_u32_e32 v93, v97, v68
	v_cvt_pk_bf16_f32 v158, v166, v188
	v_pk_add_f32 v[208:209], v[196:197], v[162:163]
	v_mov_b32_e32 v166, v187
	v_add_u32_e32 v95, 0x2000, v93
	v_cvt_pk_bf16_f32 v159, v168, v194
	v_cvt_pk_bf16_f32 v160, v174, v196
	v_cvt_pk_bf16_f32 v161, v176, v198
	v_pk_add_f32 v[170:171], v[176:177], v[208:209]
	v_pk_mul_f32 v[8:9], v[8:9], v[166:167] op_sel_hi:[1,0]
	v_pk_mul_f32 v[6:7], v[6:7], v[166:167] op_sel_hi:[1,0]
	v_pk_mul_f32 v[4:5], v[4:5], v[166:167] op_sel_hi:[1,0]
	v_pk_mul_f32 v[2:3], v[2:3], v[166:167] op_sel_hi:[1,0]
	v_pk_mul_f32 v[12:13], v[12:13], v[166:167] op_sel_hi:[1,0]
	v_pk_mul_f32 v[10:11], v[10:11], v[166:167] op_sel_hi:[1,0]
	v_pk_mul_f32 v[16:17], v[16:17], v[166:167] op_sel_hi:[1,0]
	v_pk_mul_f32 v[14:15], v[14:15], v[166:167] op_sel_hi:[1,0]
	v_cvt_pk_bf16_f32 v166, v167, v189
	v_cvt_pk_bf16_f32 v167, v169, v195
	v_cvt_pk_bf16_f32 v168, v175, v197
	v_cvt_pk_bf16_f32 v169, v177, v199
	ds_read2_b64 v[174:177], v95 offset0:128 offset1:132
	v_pk_mul_f32 v[28:29], v[28:29], v[186:187] op_sel_hi:[1,0]
	v_pk_mul_f32 v[26:27], v[26:27], v[186:187] op_sel_hi:[1,0]
	v_pk_add_f32 v[170:171], v[198:199], v[170:171]
	s_waitcnt lgkmcnt(0)
	v_mfma_f32_16x16x32_bf16 v[6:9], v[174:177], v[166:169], v[6:9]
	v_add_f32_e64 v170, v182, v170
	v_add_f32_e64 v171, v183, v171
	v_cvt_pk_bf16_f32 v162, v182, v200
	v_pk_add_f32 v[170:171], v[200:201], v[170:171]
	v_mfma_f32_16x16x32_bf16 v[26:29], v[174:177], v[158:161], v[26:29]
	ds_read2_b64 v[174:177], v95 offset0:136 offset1:140
	v_pk_add_f32 v[170:171], v[184:185], v[170:171]
	v_cvt_pk_bf16_f32 v163, v184, v202
	v_pk_add_f32 v[170:171], v[202:203], v[170:171]
	v_cvt_pk_bf16_f32 v164, v190, v204
	v_pk_add_f32 v[170:171], v[190:191], v[170:171]
	v_cvt_pk_bf16_f32 v165, v192, v206
	v_pk_add_f32 v[170:171], v[204:205], v[170:171]
	v_cvt_pk_bf16_f32 v172, v191, v205
	v_pk_add_f32 v[170:171], v[192:193], v[170:171]
	v_cvt_pk_bf16_f32 v173, v193, v207
	v_pk_add_f32 v[170:171], v[206:207], v[170:171]
	v_add_u32_e32 v95, 0x2800, v93
	v_pk_fma_f32 v[112:113], v[112:113], v[186:187], v[170:171]
	v_cvt_pk_bf16_f32 v170, v183, v201
	v_cvt_pk_bf16_f32 v171, v185, v203
	s_waitcnt lgkmcnt(0)
	v_mfma_f32_16x16x32_bf16 v[26:29], v[174:177], v[162:165], v[26:29]
	v_mul_f32_e64 v20, v20, v186
	v_mul_f32_e64 v21, v21, v186
	v_pk_mul_f32 v[18:19], v[18:19], v[186:187] op_sel_hi:[1,0]
	v_pk_mul_f32 v[24:25], v[24:25], v[186:187] op_sel_hi:[1,0]
	v_mfma_f32_16x16x32_bf16 v[6:9], v[174:177], v[170:173], v[6:9]
	ds_read2_b64 v[174:177], v95 offset0:160 offset1:164
	v_pk_mul_f32 v[22:23], v[22:23], v[186:187] op_sel_hi:[1,0]
	v_pk_mul_f32 v[32:33], v[32:33], v[186:187] op_sel_hi:[1,0]
	s_waitcnt lgkmcnt(0)
	v_mfma_f32_16x16x32_bf16 v[18:21], v[174:177], v[158:161], v[18:21]
	v_mul_f32_e64 v30, v30, v186
	v_mul_f32_e64 v31, v31, v186
	v_mfma_f32_16x16x32_bf16 v[2:5], v[174:177], v[166:169], v[2:5]
	ds_read2_b64 v[174:177], v95 offset0:168 offset1:172
	v_add_u32_e32 v95, 0x3000, v93
	v_add_u32_e32 v93, 0x3800, v93
	s_waitcnt lgkmcnt(0)
	v_mfma_f32_16x16x32_bf16 v[18:21], v[174:177], v[162:165], v[18:21]
	v_mfma_f32_16x16x32_bf16 v[2:5], v[174:177], v[170:173], v[2:5]
	ds_read2_b64 v[174:177], v95 offset0:192 offset1:196
	s_waitcnt lgkmcnt(0)
	v_mfma_f32_16x16x32_bf16 v[22:25], v[174:177], v[158:161], v[22:25]
	v_mfma_f32_16x16x32_bf16 v[10:13], v[174:177], v[166:169], v[10:13]
	ds_read2_b64 v[174:177], v95 offset0:200 offset1:204
	v_mov_b32_e32 v95, v66
	s_waitcnt lgkmcnt(0)
	v_mfma_f32_16x16x32_bf16 v[22:25], v[174:177], v[162:165], v[22:25]
	v_mfma_f32_16x16x32_bf16 v[10:13], v[174:177], v[170:173], v[10:13]
	ds_read2_b64 v[174:177], v93 offset0:224 offset1:228
	s_waitcnt lgkmcnt(0)
	v_mfma_f32_16x16x32_bf16 v[30:33], v[174:177], v[158:161], v[30:33]
	ds_read2_b64 v[158:161], v93 offset0:232 offset1:236
	v_mov_b32_e32 v93, v91
	s_waitcnt lgkmcnt(0)
	v_mfma_f32_16x16x32_bf16 v[14:17], v[174:177], v[166:169], v[14:17]
	s_barrier
	v_mfma_f32_16x16x32_bf16 v[30:33], v[158:161], v[162:165], v[30:33]
	v_mfma_f32_16x16x32_bf16 v[14:17], v[158:161], v[170:173], v[14:17]
.Lattpf_a1_b:
	s_add_i32 s11, s12, 1
	s_bitcmp1_b32 s11, 0
	s_cselect_b32 s13, 0x4800, 0
	v_add_u32_e32 v66, s13, v69
	s_min_i32 s13, s11, 21
	s_lshl_b32 s14, s13, 6
	s_waitcnt vmcnt(7)
	ds_write_b128 v66, v[216:219]
	s_waitcnt vmcnt(6)
	ds_write_b128 v66, v[220:223] offset:9216
	s_waitcnt vmcnt(5)
	ds_write_b128 v66, v[224:227] offset:4608
	s_waitcnt vmcnt(4)
	ds_write_b128 v66, v[228:231] offset:13824
	v_add_lshl_u32 v66, s14, v153, 9
	s_lshl_b32 s96, s13, 7
	v_lshl_add_u64 v[224:225], v[116:117], 0, v[66:67]
	v_lshl_add_u64 v[228:229], v[118:119], 0, s[96:97]
	s_bitcmp1_b32 s12, 0
	global_load_dwordx4 v[216:219], v[224:225], off
	global_load_dwordx4 v[220:223], v[228:229], off offset:256
	v_add_co_u32_e32 v224, vcc, s9, v224
	s_cselect_b32 s12, 0x4800, 0
	s_nop 0
	v_addc_co_u32_e32 v225, vcc, 0, v225, vcc
	s_add_i32 s12, s12, 32
	v_add_co_u32_e32 v228, vcc, s28, v228
	v_add_u32_e32 v97, s12, v152
	s_nop 0
	v_addc_co_u32_e32 v229, vcc, 0, v229, vcc
	v_lshl_add_u32 v66, v68, 1, v97
	global_load_dwordx4 v[224:227], v[224:225], off
	s_cmp_lg_u32 s11, 24
	global_load_dwordx4 v[228:231], v[228:229], off offset:256
	ds_read_b128 v[158:161], v66
	ds_read_b128 v[162:165], v66 offset:64
	s_waitcnt lgkmcnt(1)
	v_mfma_f32_16x16x32_bf16 v[166:169], v[158:161], v[34:37], 0
	s_mov_b32 s12, s11
	v_mfma_f32_16x16x32_bf16 v[158:161], v[158:161], v[46:49], 0
	s_waitcnt lgkmcnt(0)
	v_mfma_f32_16x16x32_bf16 v[166:169], v[162:165], v[42:45], v[166:169]
	v_mfma_f32_16x16x32_bf16 v[158:161], v[162:165], v[38:41], v[158:161]
	ds_read_b128 v[162:165], v66 offset:2304
	ds_read_b128 v[170:173], v66 offset:2368
	s_nop 4
	v_mul_f32_e32 v91, 0x3fb8aa3b, v167
	v_mul_f32_e32 v99, 0x3fb8aa3b, v169
	s_waitcnt lgkmcnt(1)
	v_mfma_f32_16x16x32_bf16 v[174:177], v[162:165], v[34:37], 0
	v_mfma_f32_16x16x32_bf16 v[162:165], v[162:165], v[46:49], 0
	s_waitcnt lgkmcnt(0)
	v_mfma_f32_16x16x32_bf16 v[174:177], v[170:173], v[42:45], v[174:177]
	v_mfma_f32_16x16x32_bf16 v[162:165], v[170:173], v[38:41], v[162:165]
	ds_read_b128 v[170:173], v66 offset:4608
	ds_read_b128 v[178:181], v66 offset:4672
	s_waitcnt lgkmcnt(1)
	v_mfma_f32_16x16x32_bf16 v[182:185], v[170:173], v[34:37], 0
	v_mfma_f32_16x16x32_bf16 v[170:173], v[170:173], v[46:49], 0
	s_waitcnt lgkmcnt(0)
	v_mfma_f32_16x16x32_bf16 v[182:185], v[178:181], v[42:45], v[182:185]
	v_mfma_f32_16x16x32_bf16 v[170:173], v[178:181], v[38:41], v[170:173]
	ds_read_b128 v[178:181], v66 offset:6912
	ds_read_b128 v[186:189], v66 offset:6976
	v_mul_f32_e32 v66, 0x3fb8aa3b, v166
	v_max3_f32 v66, v66, s29, v91
	s_waitcnt lgkmcnt(1)
	v_mfma_f32_16x16x32_bf16 v[190:193], v[178:181], v[34:37], 0
	v_mul_f32_e32 v91, 0x3fb8aa3b, v168
	v_max3_f32 v66, v66, v91, v99
	v_mul_f32_e32 v91, 0x3fb8aa3b, v174
	s_waitcnt lgkmcnt(0)
	v_mfma_f32_16x16x32_bf16 v[190:193], v[186:189], v[42:45], v[190:193]
	v_mul_f32_e32 v99, 0x3fb8aa3b, v175
	v_max3_f32 v66, v66, v91, v99
	v_mul_f32_e32 v91, 0x3fb8aa3b, v176
	v_mul_f32_e32 v99, 0x3fb8aa3b, v177
	v_max3_f32 v66, v66, v91, v99
	v_mul_f32_e32 v91, 0x3fb8aa3b, v182
	v_mul_f32_e32 v99, 0x3fb8aa3b, v183
	v_max3_f32 v66, v66, v91, v99
	v_mul_f32_e32 v91, 0x3fb8aa3b, v184
	v_mul_f32_e32 v99, 0x3fb8aa3b, v185
	v_max3_f32 v66, v66, v91, v99
	v_mul_f32_e32 v91, 0x3fb8aa3b, v190
	v_mul_f32_e32 v99, 0x3fb8aa3b, v191
	v_max3_f32 v66, v66, v91, v99
	v_mul_f32_e32 v91, 0x3fb8aa3b, v192
	v_mul_f32_e32 v99, 0x3fb8aa3b, v193
	v_max3_f32 v66, v66, v91, v99
	ds_bpermute_b32 v91, v89, v66
	v_mfma_f32_16x16x32_bf16 v[178:181], v[178:181], v[46:49], 0
	v_mul_f32_e32 v99, 0x3fb8aa3b, v161
	s_waitcnt lgkmcnt(0)
	v_max_f32_e32 v91, v91, v91
	v_max_f32_e32 v66, v66, v91
	ds_bpermute_b32 v91, v87, v66
	v_mfma_f32_16x16x32_bf16 v[178:181], v[186:189], v[38:41], v[178:181]
	s_waitcnt lgkmcnt(0)
	v_max3_f32 v66, v95, v66, v91
	v_sub_f32_e32 v91, v95, v66
	v_exp_f32_e32 v186, v91
	v_fma_f32 v91, v166, s27, -v66
	v_exp_f32_e32 v166, v91
	v_fma_f32 v91, v167, s27, -v66
	v_exp_f32_e32 v188, v91
	v_fma_f32 v91, v168, s27, -v66
	v_exp_f32_e32 v168, v91
	v_fma_f32 v91, v169, s27, -v66
	v_exp_f32_e32 v194, v91
	v_fma_f32 v91, v174, s27, -v66
	v_exp_f32_e32 v174, v91
	v_fma_f32 v91, v175, s27, -v66
	v_exp_f32_e32 v196, v91
	v_fma_f32 v91, v176, s27, -v66
	v_exp_f32_e32 v176, v91
	v_fma_f32 v91, v177, s27, -v66
	v_exp_f32_e32 v198, v91
	v_fma_f32 v91, v182, s27, -v66
	v_exp_f32_e32 v182, v91
	v_fma_f32 v91, v183, s27, -v66
	v_exp_f32_e32 v200, v91
	v_fma_f32 v91, v184, s27, -v66
	v_exp_f32_e32 v184, v91
	v_fma_f32 v91, v185, s27, -v66
	v_exp_f32_e32 v202, v91
	v_fma_f32 v91, v190, s27, -v66
	v_exp_f32_e32 v190, v91
	v_fma_f32 v91, v191, s27, -v66
	v_exp_f32_e32 v204, v91
	v_fma_f32 v91, v192, s27, -v66
	v_exp_f32_e32 v192, v91
	v_fma_f32 v91, v193, s27, -v66
	v_exp_f32_e32 v206, v91
	v_mul_f32_e32 v91, 0x3fb8aa3b, v158
	v_mul_f32_e32 v95, 0x3fb8aa3b, v159
	v_max3_f32 v91, v91, s29, v95
	v_mul_f32_e32 v95, 0x3fb8aa3b, v160
	v_max3_f32 v91, v91, v95, v99
	v_mul_f32_e32 v95, 0x3fb8aa3b, v162
	v_mul_f32_e32 v99, 0x3fb8aa3b, v163
	v_max3_f32 v91, v91, v95, v99
	v_mul_f32_e32 v95, 0x3fb8aa3b, v164
	v_mul_f32_e32 v99, 0x3fb8aa3b, v165
	v_max3_f32 v91, v91, v95, v99
	v_mul_f32_e32 v95, 0x3fb8aa3b, v170
	v_mul_f32_e32 v99, 0x3fb8aa3b, v171
	v_max3_f32 v91, v91, v95, v99
	v_mul_f32_e32 v95, 0x3fb8aa3b, v172
	v_mul_f32_e32 v99, 0x3fb8aa3b, v173
	v_max3_f32 v91, v91, v95, v99
	v_mul_f32_e32 v95, 0x3fb8aa3b, v178
	v_mul_f32_e32 v99, 0x3fb8aa3b, v179
	v_max3_f32 v91, v91, v95, v99
	v_mul_f32_e32 v95, 0x3fb8aa3b, v180
	v_mul_f32_e32 v99, 0x3fb8aa3b, v181
	v_max3_f32 v91, v91, v95, v99
	ds_bpermute_b32 v95, v89, v91
	s_waitcnt lgkmcnt(0)
	v_max_f32_e32 v95, v95, v95
	v_max_f32_e32 v91, v91, v95
	ds_bpermute_b32 v95, v87, v91
	s_waitcnt lgkmcnt(0)
	v_max3_f32 v91, v93, v91, v95
	v_sub_f32_e32 v93, v93, v91
	v_exp_f32_e32 v187, v93
	v_fma_f32 v93, v158, s27, -v91
	v_exp_f32_e32 v167, v93
	v_fma_f32 v93, v159, s27, -v91
	v_exp_f32_e32 v189, v93
	v_fma_f32 v93, v160, s27, -v91
	v_exp_f32_e32 v169, v93
	v_fma_f32 v93, v161, s27, -v91
	v_exp_f32_e32 v195, v93
	v_fma_f32 v93, v162, s27, -v91
	v_exp_f32_e32 v175, v93
	v_fma_f32 v93, v163, s27, -v91
	v_exp_f32_e32 v197, v93
	v_fma_f32 v93, v164, s27, -v91
	v_exp_f32_e32 v177, v93
	v_fma_f32 v93, v165, s27, -v91
	v_exp_f32_e32 v199, v93
	v_fma_f32 v93, v170, s27, -v91
	v_exp_f32_e32 v183, v93
	v_fma_f32 v93, v171, s27, -v91
	v_exp_f32_e32 v201, v93
	v_fma_f32 v93, v172, s27, -v91
	v_exp_f32_e32 v185, v93
	v_fma_f32 v93, v173, s27, -v91
	v_pk_add_f32 v[162:163], v[166:167], 0 op_sel_hi:[1,0]
	v_exp_f32_e32 v203, v93
	v_fma_f32 v93, v178, s27, -v91
	v_pk_add_f32 v[162:163], v[188:189], v[162:163]
	v_exp_f32_e32 v191, v93
	v_fma_f32 v93, v179, s27, -v91
	v_pk_add_f32 v[162:163], v[168:169], v[162:163]
	v_exp_f32_e32 v205, v93
	v_fma_f32 v93, v180, s27, -v91
	v_pk_add_f32 v[162:163], v[194:195], v[162:163]
	v_exp_f32_e32 v193, v93
	v_fma_f32 v93, v181, s27, -v91
	v_pk_add_f32 v[162:163], v[174:175], v[162:163]
	v_exp_f32_e32 v207, v93
	v_add_u32_e32 v93, v97, v68
	v_cvt_pk_bf16_f32 v158, v166, v188
	v_pk_add_f32 v[208:209], v[196:197], v[162:163]
	v_mov_b32_e32 v166, v187
	v_add_u32_e32 v95, 0x2000, v93
	v_cvt_pk_bf16_f32 v159, v168, v194
	v_cvt_pk_bf16_f32 v160, v174, v196
	v_cvt_pk_bf16_f32 v161, v176, v198
	v_pk_add_f32 v[170:171], v[176:177], v[208:209]
	v_pk_mul_f32 v[8:9], v[8:9], v[166:167] op_sel_hi:[1,0]
	v_pk_mul_f32 v[6:7], v[6:7], v[166:167] op_sel_hi:[1,0]
	v_pk_mul_f32 v[4:5], v[4:5], v[166:167] op_sel_hi:[1,0]
	v_pk_mul_f32 v[2:3], v[2:3], v[166:167] op_sel_hi:[1,0]
	v_pk_mul_f32 v[12:13], v[12:13], v[166:167] op_sel_hi:[1,0]
	v_pk_mul_f32 v[10:11], v[10:11], v[166:167] op_sel_hi:[1,0]
	v_pk_mul_f32 v[16:17], v[16:17], v[166:167] op_sel_hi:[1,0]
	v_pk_mul_f32 v[14:15], v[14:15], v[166:167] op_sel_hi:[1,0]
	v_cvt_pk_bf16_f32 v166, v167, v189
	v_cvt_pk_bf16_f32 v167, v169, v195
	v_cvt_pk_bf16_f32 v168, v175, v197
	v_cvt_pk_bf16_f32 v169, v177, v199
	ds_read2_b64 v[174:177], v95 offset0:128 offset1:132
	v_pk_mul_f32 v[28:29], v[28:29], v[186:187] op_sel_hi:[1,0]
	v_pk_mul_f32 v[26:27], v[26:27], v[186:187] op_sel_hi:[1,0]
	v_pk_add_f32 v[170:171], v[198:199], v[170:171]
	s_waitcnt lgkmcnt(0)
	v_mfma_f32_16x16x32_bf16 v[6:9], v[174:177], v[166:169], v[6:9]
	v_add_f32_e64 v170, v182, v170
	v_add_f32_e64 v171, v183, v171
	v_cvt_pk_bf16_f32 v162, v182, v200
	v_pk_add_f32 v[170:171], v[200:201], v[170:171]
	v_mfma_f32_16x16x32_bf16 v[26:29], v[174:177], v[158:161], v[26:29]
	ds_read2_b64 v[174:177], v95 offset0:136 offset1:140
	v_pk_add_f32 v[170:171], v[184:185], v[170:171]
	v_cvt_pk_bf16_f32 v163, v184, v202
	v_pk_add_f32 v[170:171], v[202:203], v[170:171]
	v_cvt_pk_bf16_f32 v164, v190, v204
	v_pk_add_f32 v[170:171], v[190:191], v[170:171]
	v_cvt_pk_bf16_f32 v165, v192, v206
	v_pk_add_f32 v[170:171], v[204:205], v[170:171]
	v_cvt_pk_bf16_f32 v172, v191, v205
	v_pk_add_f32 v[170:171], v[192:193], v[170:171]
	v_cvt_pk_bf16_f32 v173, v193, v207
	v_pk_add_f32 v[170:171], v[206:207], v[170:171]
	v_add_u32_e32 v95, 0x2800, v93
	v_pk_fma_f32 v[112:113], v[112:113], v[186:187], v[170:171]
	v_cvt_pk_bf16_f32 v170, v183, v201
	v_cvt_pk_bf16_f32 v171, v185, v203
	s_waitcnt lgkmcnt(0)
	v_mfma_f32_16x16x32_bf16 v[26:29], v[174:177], v[162:165], v[26:29]
	v_mul_f32_e64 v20, v20, v186
	v_mul_f32_e64 v21, v21, v186
	v_pk_mul_f32 v[18:19], v[18:19], v[186:187] op_sel_hi:[1,0]
	v_pk_mul_f32 v[24:25], v[24:25], v[186:187] op_sel_hi:[1,0]
	v_mfma_f32_16x16x32_bf16 v[6:9], v[174:177], v[170:173], v[6:9]
	ds_read2_b64 v[174:177], v95 offset0:160 offset1:164
	v_pk_mul_f32 v[22:23], v[22:23], v[186:187] op_sel_hi:[1,0]
	v_pk_mul_f32 v[32:33], v[32:33], v[186:187] op_sel_hi:[1,0]
	s_waitcnt lgkmcnt(0)
	v_mfma_f32_16x16x32_bf16 v[18:21], v[174:177], v[158:161], v[18:21]
	v_mul_f32_e64 v30, v30, v186
	v_mul_f32_e64 v31, v31, v186
	v_mfma_f32_16x16x32_bf16 v[2:5], v[174:177], v[166:169], v[2:5]
	ds_read2_b64 v[174:177], v95 offset0:168 offset1:172
	v_add_u32_e32 v95, 0x3000, v93
	v_add_u32_e32 v93, 0x3800, v93
	s_waitcnt lgkmcnt(0)
	v_mfma_f32_16x16x32_bf16 v[18:21], v[174:177], v[162:165], v[18:21]
	v_mfma_f32_16x16x32_bf16 v[2:5], v[174:177], v[170:173], v[2:5]
	ds_read2_b64 v[174:177], v95 offset0:192 offset1:196
	s_waitcnt lgkmcnt(0)
	v_mfma_f32_16x16x32_bf16 v[22:25], v[174:177], v[158:161], v[22:25]
	v_mfma_f32_16x16x32_bf16 v[10:13], v[174:177], v[166:169], v[10:13]
	ds_read2_b64 v[174:177], v95 offset0:200 offset1:204
	v_mov_b32_e32 v95, v66
	s_waitcnt lgkmcnt(0)
	v_mfma_f32_16x16x32_bf16 v[22:25], v[174:177], v[162:165], v[22:25]
	v_mfma_f32_16x16x32_bf16 v[10:13], v[174:177], v[170:173], v[10:13]
	ds_read2_b64 v[174:177], v93 offset0:224 offset1:228
	s_waitcnt lgkmcnt(0)
	v_mfma_f32_16x16x32_bf16 v[30:33], v[174:177], v[158:161], v[30:33]
	ds_read2_b64 v[158:161], v93 offset0:232 offset1:236
	v_mov_b32_e32 v93, v91
	s_waitcnt lgkmcnt(0)
	v_mfma_f32_16x16x32_bf16 v[14:17], v[174:177], v[166:169], v[14:17]
	s_barrier
	v_mfma_f32_16x16x32_bf16 v[30:33], v[158:161], v[162:165], v[30:33]
	v_mfma_f32_16x16x32_bf16 v[14:17], v[158:161], v[170:173], v[14:17]
	s_cbranch_scc1 .LBB0_1088
	s_waitcnt vmcnt(0)
	ds_bpermute_b32 v37, v89, v112
	s_lshl_b32 s96, s10, 1
	v_or_b32_e32 v36, v114, v141
	v_lshl_add_u64 v[34:35], v[84:85], 0, s[96:97]
	s_waitcnt lgkmcnt(0)
	v_add_f32_e32 v37, v112, v37
	ds_bpermute_b32 v38, v87, v37
	s_waitcnt lgkmcnt(0)
	v_add_f32_e32 v37, v37, v38
	v_div_scale_f32 v38, s[10:11], v37, v37, 1.0
	v_rcp_f32_e32 v39, v38
	s_nop 0
	v_fma_f32 v40, -v38, v39, 1.0
	v_fmac_f32_e32 v39, v40, v39
	v_div_scale_f32 v40, vcc, 1.0, v37, 1.0
	v_mul_f32_e32 v41, v40, v39
	v_fma_f32 v42, -v38, v41, v40
	v_fmac_f32_e32 v41, v42, v39
	v_fma_f32 v38, -v38, v41, v40
	v_div_fmas_f32 v38, v38, v39, v41
	v_div_fixup_f32 v38, v38, v37, 1.0
	v_ashrrev_i32_e32 v37, 31, v36
	v_lshlrev_b64 v[40:41], 11, v[36:37]
	v_pk_mul_f32 v[18:19], v[18:19], v[38:39] op_sel_hi:[1,0]
	v_pk_mul_f32 v[20:21], v[20:21], v[38:39] op_sel_hi:[1,0]
	v_lshl_add_u64 v[40:41], v[34:35], 0, v[40:41]
	v_cvt_pk_bf16_f32 v18, v18, v19
	v_cvt_pk_bf16_f32 v19, v20, v21
	global_store_dwordx2 v[40:41], v[18:19], off offset:32
	v_pk_mul_f32 v[18:19], v[22:23], v[38:39] op_sel_hi:[1,0]
	v_pk_mul_f32 v[20:21], v[24:25], v[38:39] op_sel_hi:[1,0]
	v_cvt_pk_bf16_f32 v18, v18, v19
	v_cvt_pk_bf16_f32 v19, v20, v21
	global_store_dwordx2 v[40:41], v[18:19], off offset:64
	v_pk_mul_f32 v[18:19], v[30:31], v[38:39] op_sel_hi:[1,0]
	v_pk_mul_f32 v[20:21], v[32:33], v[38:39] op_sel_hi:[1,0]
	v_cvt_pk_bf16_f32 v18, v18, v19
	v_cvt_pk_bf16_f32 v19, v20, v21
	global_store_dwordx2 v[40:41], v[18:19], off offset:96
	ds_bpermute_b32 v18, v89, v113
	v_pk_mul_f32 v[26:27], v[26:27], v[38:39] op_sel_hi:[1,0]
	v_pk_mul_f32 v[28:29], v[28:29], v[38:39] op_sel_hi:[1,0]
	v_cvt_pk_bf16_f32 v26, v26, v27
	v_cvt_pk_bf16_f32 v27, v28, v29
	s_waitcnt lgkmcnt(0)
	v_add_f32_e32 v18, v113, v18
	ds_bpermute_b32 v19, v87, v18
	global_store_dwordx2 v[40:41], v[26:27], off
	s_waitcnt lgkmcnt(0)
	v_add_f32_e32 v18, v18, v19
	v_div_scale_f32 v19, s[10:11], v18, v18, 1.0
	v_rcp_f32_e32 v20, v19
	s_nop 0
	v_fma_f32 v21, -v19, v20, 1.0
	v_fmac_f32_e32 v20, v21, v20
	v_div_scale_f32 v21, vcc, 1.0, v18, 1.0
	v_mul_f32_e32 v22, v21, v20
	v_fma_f32 v23, -v19, v22, v21
	v_fmac_f32_e32 v22, v23, v20
	v_fma_f32 v19, -v19, v22, v21
	v_div_fmas_f32 v19, v19, v20, v22
	v_or_b32_e32 v20, 16, v36
	v_div_fixup_f32 v18, v19, v18, 1.0
	v_ashrrev_i32_e32 v21, 31, v20
	v_lshlrev_b64 v[20:21], 11, v[20:21]
	v_pk_mul_f32 v[2:3], v[2:3], v[18:19] op_sel_hi:[1,0]
	v_pk_mul_f32 v[4:5], v[4:5], v[18:19] op_sel_hi:[1,0]
	v_lshl_add_u64 v[20:21], v[34:35], 0, v[20:21]
	v_cvt_pk_bf16_f32 v2, v2, v3
	v_cvt_pk_bf16_f32 v3, v4, v5
	global_store_dwordx2 v[20:21], v[2:3], off offset:32
	v_pk_mul_f32 v[2:3], v[10:11], v[18:19] op_sel_hi:[1,0]
	v_pk_mul_f32 v[4:5], v[12:13], v[18:19] op_sel_hi:[1,0]
	v_cvt_pk_bf16_f32 v2, v2, v3
	v_cvt_pk_bf16_f32 v3, v4, v5
	v_pk_mul_f32 v[6:7], v[6:7], v[18:19] op_sel_hi:[1,0]
	v_pk_mul_f32 v[8:9], v[8:9], v[18:19] op_sel_hi:[1,0]
	global_store_dwordx2 v[20:21], v[2:3], off offset:64
	v_pk_mul_f32 v[2:3], v[14:15], v[18:19] op_sel_hi:[1,0]
	v_pk_mul_f32 v[4:5], v[16:17], v[18:19] op_sel_hi:[1,0]
	v_cvt_pk_bf16_f32 v6, v6, v7
	v_cvt_pk_bf16_f32 v7, v8, v9
	v_cvt_pk_bf16_f32 v2, v2, v3
	v_cvt_pk_bf16_f32 v3, v4, v5
	global_store_dwordx2 v[20:21], v[6:7], off
	global_store_dwordx2 v[20:21], v[2:3], off offset:96
	s_branch .LBB0_1053
